# GEMM phases: static priority 1 for blocks < 256 of each CU pair, all per-segment s_setprio flips in the tile loops removed
# baseline (speedup 1.0000x reference)
; __device__ __forceinline__ void run_phase(const Params& p, int ph, char* lds, int mode) {
;     ...
;   if (ph == 15) { final_norm_rows(p); return; }
;   const int l = (ph - 1) / 7, sp = (ph - 1) % 7;
; __global__ void __launch_bounds__(NTHREADS, 2) mk_fwd(Params p) {
;     ...
;   for (int i = 0; i < nsteps; i++) {
;     int ph = p.phase_lo + i, mode = 0;
;     if (PROBE_PH >= 0 && ph > PROBE_PH) { ph -= 1; if (ph == PROBE_PH) mode = PROBE_MODE; }
;     if (i > 0) xcd_barrier(xb);
;     run_phase(p, ph, lds, mode);
.LBB0_76:
	s_setprio 0
	v_readlane_b32 s2, v252, 51
	v_readlane_b32 s3, v252, 52
	s_waitcnt lgkmcnt(0)
	s_load_dword s77, s[2:3], 0x0
	v_readlane_b32 s2, v252, 1
	s_add_i32 s2, s76, s2
	s_mov_b64 s[28:29], -1
	s_mov_b64 s[24:25], 0
	s_cmp_lt_i32 s2, 15
	s_mov_b64 s[26:27], 0
	v_readlane_b32 s3, v252, 2
	s_cbranch_scc0 .LBB0_80
	s_and_b64 vcc, exec, s[28:29]
	s_cbranch_vccnz .LBB0_86

; __global__ void __launch_bounds__(NTHREADS, 2) mk_fwd(Params p) {
;     ...
;   for (int i = 0; i < nsteps; i++) {
;     int ph = p.phase_lo + i, mode = 0;
;     if (PROBE_PH >= 0 && ph > PROBE_PH) { ph -= 1; if (ph == PROBE_PH) mode = PROBE_MODE; }
;     if (i > 0) xcd_barrier(xb);
;     run_phase(p, ph, lds, mode);
.Lxcd_skip1:
	v_readlane_b32 vcc_lo, v252, 0
	s_nop 0
	s_cmpk_lt_u32 vcc_lo, 0x100
	s_cbranch_scc0 .Lmy_sp_f
	s_setprio 1

; __device__ __forceinline__ void gemm_mainloop_d(const bf16_t* __restrict__ Ap, int lda, const bf16_t* __restrict__ Bt, int K,
;                                                 int m0, int n0, f32x4 (&acc)[4][4], char* lds) {
;     ...
;   auto dma = [&](int kt, int st) {
;     char* la = lds + st * 32768; char* lb = la + 16384;
; #pragma unroll
;     for (int i = 0; i < 4; i++) {
;       const int row = i * 32 + lrow; const int c = cph ^ ((row >> 1) & 7);
;       __builtin_amdgcn_global_load_lds((const unsigned*)(Ap + (size_t)(m0 + row) * lda + kt * 64 + c * 8), (__attribute__((address_space(3))) unsigned*)(la + i * 4096 + tid * 16), 16, 0, 0);
;       __builtin_amdgcn_global_load_lds((const unsigned*)(Bt + (size_t)(n0 + row) * K + kt * 64 + c * 8), (__attribute__((address_space(3))) unsigned*)(lb + i * 4096 + tid * 16), 16, 0, 0);
;     }
;   };
;   dma(0, 0);
;   asm volatile("s_waitcnt vmcnt(0)" ::: "memory"); __builtin_amdgcn_s_barrier(); asm volatile("" ::: "memory");
;   for (int kt = 0; kt < nk; kt++) {
;     const int st = kt & 1;
;     if (kt + 1 < nk) dma(kt + 1, st ^ 1);
;     const char* la = lds + st * 32768; const char* lb = la + 16384;
;     bf16x8 af[2][4], bfv[2][4];
; #pragma unroll
;     for (int kc = 0; kc < 2; kc++) {
; #pragma unroll
;       for (int m = 0; m < 4; m++) { const int row = wr * 64 + m * 16 + fr; af[kc][m] = *(const bf16x8*)(la + (row * 8 + ((kc * 4 + fq) ^ ((row >> 1) & 7))) * 16); }
; #pragma unroll
;       for (int n = 0; n < 4; n++) { const int row = wc * 64 + n * 16 + fr; bfv[kc][n] = *(const bf16x8*)(lb + (row * 8 + ((kc * 4 + fq) ^ ((row >> 1) & 7))) * 16); }
;     }
;     __builtin_amdgcn_s_setprio(1);
; #pragma unroll
;     for (int kc = 0; kc < 2; kc++)
; #pragma unroll
;       for (int m = 0; m < 4; m++)
; #pragma unroll
;         for (int n = 0; n < 4; n++) acc[m][n] = __builtin_amdgcn_mfma_f32_16x16x32_bf16(bfv[kc][n], af[kc][m], acc[m][n], 0, 0, 0);
;     __builtin_amdgcn_s_setprio(0);
;     asm volatile("s_waitcnt vmcnt(0) lgkmcnt(0)" ::: "memory"); __builtin_amdgcn_s_barrier(); asm volatile("" ::: "memory");
;   }
.LBB0_95:
	s_and_b32 s29, s26, 0x8000
	s_xor_b32 s37, s29, 0x8000
	s_add_i32 s37, s37, vcc_hi
	s_mov_b32 m0, s37
	s_add_i32 vcc_lo, s37, 0x4000
	global_load_lds_dwordx4 v150, s[46:47]
	s_mov_b32 m0, vcc_lo
	s_add_i32 vcc_lo, s37, 0x1000
	global_load_lds_dwordx4 v151, s[46:47]
	s_mov_b32 m0, vcc_lo
	s_add_i32 vcc_lo, s37, 0x5000
	global_load_lds_dwordx4 v152, s[46:47]
	s_mov_b32 m0, vcc_lo
	s_add_i32 vcc_lo, s37, 0x2000
	global_load_lds_dwordx4 v153, s[46:47]
	s_mov_b32 m0, vcc_lo
	s_add_i32 vcc_lo, s37, 0x6000
	global_load_lds_dwordx4 v154, s[46:47]
	s_mov_b32 m0, vcc_lo
	s_add_i32 vcc_lo, s37, 0x3000
	global_load_lds_dwordx4 v155, s[46:47]
	s_mov_b32 m0, vcc_lo
	s_add_i32 vcc_lo, s37, 0x7000
	global_load_lds_dwordx4 v156, s[46:47]
	s_mov_b32 m0, vcc_lo
	s_nop 0
	global_load_lds_dwordx4 v157, s[46:47]
	v_add_u32_e32 v150, 0x80, v150
	v_add_u32_e32 v151, 0x80, v151
	v_add_u32_e32 v152, 0x80, v152
	v_add_u32_e32 v153, 0x80, v153
	v_add_u32_e32 v154, 0x80, v154
	v_add_u32_e32 v155, 0x80, v155
	v_add_u32_e32 v156, 0x80, v156
	v_add_u32_e32 v157, 0x80, v157
	v_add_u32_e32 v98, s29, v85
	v_add_u32_e32 v114, s29, v84
	v_add_u32_e32 v130, s29, v83
	v_add_u32_e32 v146, s29, v2
	ds_read_b128 v[86:89], v98
	ds_read_b128 v[90:93], v98 offset:2048
	ds_read_b128 v[94:97], v98 offset:4096
	ds_read_b128 v[98:101], v98 offset:6144
	ds_read_b128 v[102:105], v114 offset:16384
	ds_read_b128 v[106:109], v114 offset:18432
	ds_read_b128 v[110:113], v114 offset:20480
	ds_read_b128 v[114:117], v114 offset:22528
	ds_read_b128 v[118:121], v130
	ds_read_b128 v[122:125], v130 offset:2048
	ds_read_b128 v[126:129], v130 offset:4096
	ds_read_b128 v[130:133], v130 offset:6144
	ds_read_b128 v[134:137], v146 offset:16384
	ds_read_b128 v[138:141], v146 offset:18432
	ds_read_b128 v[142:145], v146 offset:20480
	ds_read_b128 v[146:149], v146 offset:22528
	s_waitcnt lgkmcnt(0)
	v_mfma_f32_16x16x32_bf16 v[64:67], v[102:105], v[86:89], v[64:67]
	v_mfma_f32_16x16x32_bf16 v[60:63], v[106:109], v[86:89], v[60:63]
	v_mfma_f32_16x16x32_bf16 v[56:59], v[110:113], v[86:89], v[56:59]
	v_mfma_f32_16x16x32_bf16 v[52:55], v[114:117], v[86:89], v[52:55]
	v_mfma_f32_16x16x32_bf16 v[48:51], v[102:105], v[90:93], v[48:51]
	v_mfma_f32_16x16x32_bf16 v[44:47], v[106:109], v[90:93], v[44:47]
	v_mfma_f32_16x16x32_bf16 v[40:43], v[110:113], v[90:93], v[40:43]
	v_mfma_f32_16x16x32_bf16 v[36:39], v[114:117], v[90:93], v[36:39]
	v_mfma_f32_16x16x32_bf16 v[32:35], v[102:105], v[94:97], v[32:35]
	v_mfma_f32_16x16x32_bf16 v[28:31], v[106:109], v[94:97], v[28:31]
	v_mfma_f32_16x16x32_bf16 v[24:27], v[110:113], v[94:97], v[24:27]
	v_mfma_f32_16x16x32_bf16 v[20:23], v[114:117], v[94:97], v[20:23]
	v_mfma_f32_16x16x32_bf16 v[16:19], v[102:105], v[98:101], v[16:19]
	v_mfma_f32_16x16x32_bf16 v[12:15], v[106:109], v[98:101], v[12:15]
	v_mfma_f32_16x16x32_bf16 v[8:11], v[110:113], v[98:101], v[8:11]
	v_mfma_f32_16x16x32_bf16 v[4:7], v[114:117], v[98:101], v[4:7]
	v_mfma_f32_16x16x32_bf16 v[64:67], v[134:137], v[118:121], v[64:67]
	v_mfma_f32_16x16x32_bf16 v[60:63], v[138:141], v[118:121], v[60:63]
	v_mfma_f32_16x16x32_bf16 v[56:59], v[142:145], v[118:121], v[56:59]
	v_mfma_f32_16x16x32_bf16 v[52:55], v[146:149], v[118:121], v[52:55]
	v_mfma_f32_16x16x32_bf16 v[48:51], v[134:137], v[122:125], v[48:51]
	v_mfma_f32_16x16x32_bf16 v[44:47], v[138:141], v[122:125], v[44:47]
	v_mfma_f32_16x16x32_bf16 v[40:43], v[142:145], v[122:125], v[40:43]
	v_mfma_f32_16x16x32_bf16 v[36:39], v[146:149], v[122:125], v[36:39]
	v_mfma_f32_16x16x32_bf16 v[32:35], v[134:137], v[126:129], v[32:35]
	v_mfma_f32_16x16x32_bf16 v[28:31], v[138:141], v[126:129], v[28:31]
	v_mfma_f32_16x16x32_bf16 v[24:27], v[142:145], v[126:129], v[24:27]
	v_mfma_f32_16x16x32_bf16 v[20:23], v[146:149], v[126:129], v[20:23]
	v_mfma_f32_16x16x32_bf16 v[16:19], v[134:137], v[130:133], v[16:19]
	v_mfma_f32_16x16x32_bf16 v[12:15], v[138:141], v[130:133], v[12:15]
	v_mfma_f32_16x16x32_bf16 v[8:11], v[142:145], v[130:133], v[8:11]
	v_mfma_f32_16x16x32_bf16 v[4:7], v[146:149], v[130:133], v[4:7]
	s_waitcnt vmcnt(0) lgkmcnt(0)
	s_barrier
	s_add_u32 s24, s24, 0x80
	s_addc_u32 s25, s25, 0
	s_add_i32 s26, s26, 0x8000
	s_cmpk_eq_i32 s24, 0x1580
	s_cbranch_scc0 .LBB0_95
	v_add_u32_e32 v0, 0, v85
	ds_read_b128 v[68:71], v0 offset:32768
	ds_read_b128 v[72:75], v0 offset:34816
	ds_read_b128 v[76:79], v0 offset:36864
	ds_read_b128 v[86:89], v0 offset:38912
	v_add_u32_e32 v0, 0, v84
	ds_read_b128 v[90:93], v0 offset:49152
	ds_read_b128 v[94:97], v0 offset:51200
	ds_read_b128 v[98:101], v0 offset:53248
	ds_read_b128 v[102:105], v0 offset:55296
	v_add_u32_e32 v0, 0, v83
	s_add_u32 s24, s46, s27
	ds_read_b128 v[80:83], v0 offset:32768
	ds_read_b128 v[106:109], v0 offset:34816
	ds_read_b128 v[110:113], v0 offset:36864
	ds_read_b128 v[114:117], v0 offset:38912
	v_add_u32_e32 v0, 0, v2
	s_addc_u32 s25, s47, 0
	ds_read_b128 v[118:121], v0 offset:49152
	ds_read_b128 v[122:125], v0 offset:51200
	ds_read_b128 v[126:129], v0 offset:53248
	ds_read_b128 v[130:133], v0 offset:55296
	s_add_u32 s28, s46, s28
	s_addc_u32 s29, s47, 0
	s_add_u32 s26, s24, 0x65a8000
	s_addc_u32 s27, s25, 0
	s_add_u32 s24, s28, 0xff8c000
	s_addc_u32 s25, s29, 0
	s_waitcnt lgkmcnt(0)
; __device__ __forceinline__ unsigned pk2(float lo, float hi) { unsigned r; asm("v_cvt_pk_bf16_f32 %0, %1, %2" : "=v"(r) : "v"(lo), "v"(hi)); return r; }
; __device__ __forceinline__ float bflo(unsigned u) { return __uint_as_float(u << 16); }
; __device__ __forceinline__ float bfhi(unsigned u) { return __uint_as_float(u & 0xffff0000u); }
; __device__ __forceinline__ void gemm_mainloop_d(const bf16_t* __restrict__ Ap, int lda, const bf16_t* __restrict__ Bt, int K,
;                                                 int m0, int n0, f32x4 (&acc)[4][4], char* lds) {
;     ...
;     for (int kc = 0; kc < 2; kc++)
; #pragma unroll
;       for (int m = 0; m < 4; m++)
; #pragma unroll
;         for (int n = 0; n < 4; n++) acc[m][n] = __builtin_amdgcn_mfma_f32_16x16x32_bf16(bfv[kc][n], af[kc][m], acc[m][n], 0, 0, 0);
;     __builtin_amdgcn_s_setprio(0);
;     asm volatile("s_waitcnt vmcnt(0) lgkmcnt(0)" ::: "memory"); __builtin_amdgcn_s_barrier(); asm volatile("" ::: "memory");
; __device__ __forceinline__ void gemm_RES(const bf16_t* A, int K, const bf16_t* Bt, const float* xin, float* xout, bf16_t* xb, float* rss, int item, char* lds) {
;     ...
; #pragma unroll
;   for (int m = 0; m < 4; m++) {
;     const int rowg = m0 + wr * 64 + m * 16 + fr;
;     const size_t ro = (size_t)rowg * DM;
;     float sq = 0.f;
; #pragma unroll
;     for (int n = 0; n < 4; n++) {
;       const int col = n0 + wc * 64 + n * 16 + fq * 4;
;       f32x4 xv = *(const f32x4*)(xin + ro + col);
;       const f32x4 xn = xv + acc[m][n];
;       *(f32x4*)(xout + ro + col) = xn;
;       u32x2 w; w[0] = pk2(xn[0], xn[1]); w[1] = pk2(xn[2], xn[3]); *(u32x2*)(xb + ro + col) = w;
;       const float b0 = bflo(w[0]), b1 = bfhi(w[0]), b2 = bflo(w[1]), b3 = bfhi(w[1]);
;       sq += b0 * b0 + b1 * b1 + b2 * b2 + b3 * b3;
;     }
;     sq += __shfl_xor(sq, 16); sq += __shfl_xor(sq, 32);
;     if (fq == 0) unsafeAtomicAdd(rss + rowg, sq);
;   }
	v_mfma_f32_16x16x32_bf16 v[56:59], v[98:101], v[68:71], v[56:59]
	v_mfma_f32_16x16x32_bf16 v[48:51], v[90:93], v[72:75], v[48:51]
	v_mfma_f32_16x16x32_bf16 v[44:47], v[94:97], v[72:75], v[44:47]
	v_mfma_f32_16x16x32_bf16 v[40:43], v[98:101], v[72:75], v[40:43]
	v_mfma_f32_16x16x32_bf16 v[36:39], v[102:105], v[72:75], v[36:39]
	v_mfma_f32_16x16x32_bf16 v[32:35], v[90:93], v[76:79], v[32:35]
	v_mfma_f32_16x16x32_bf16 v[28:31], v[94:97], v[76:79], v[28:31]
	v_mfma_f32_16x16x32_bf16 v[24:27], v[98:101], v[76:79], v[24:27]
	v_mfma_f32_16x16x32_bf16 v[20:23], v[102:105], v[76:79], v[20:23]
	v_mfma_f32_16x16x32_bf16 v[16:19], v[90:93], v[86:89], v[16:19]
	v_mfma_f32_16x16x32_bf16 v[12:15], v[94:97], v[86:89], v[12:15]
	v_mfma_f32_16x16x32_bf16 v[8:11], v[98:101], v[86:89], v[8:11]
	v_mfma_f32_16x16x32_bf16 v[4:7], v[102:105], v[86:89], v[4:7]
	v_mfma_f32_16x16x32_bf16 v[64:67], v[90:93], v[68:71], v[64:67]
	v_mfma_f32_16x16x32_bf16 v[60:63], v[94:97], v[68:71], v[60:63]
	v_mfma_f32_16x16x32_bf16 v[52:55], v[102:105], v[68:71], v[52:55]
	v_mfma_f32_16x16x32_bf16 v[56:59], v[126:129], v[80:83], v[56:59]
	v_mfma_f32_16x16x32_bf16 v[48:51], v[118:121], v[106:109], v[48:51]
	v_mfma_f32_16x16x32_bf16 v[44:47], v[122:125], v[106:109], v[44:47]
	v_mfma_f32_16x16x32_bf16 v[40:43], v[126:129], v[106:109], v[40:43]
	v_mfma_f32_16x16x32_bf16 v[36:39], v[130:133], v[106:109], v[36:39]
	v_mfma_f32_16x16x32_bf16 v[32:35], v[118:121], v[110:113], v[32:35]
	v_mfma_f32_16x16x32_bf16 v[28:31], v[122:125], v[110:113], v[28:31]
	v_mfma_f32_16x16x32_bf16 v[24:27], v[126:129], v[110:113], v[24:27]
	v_mfma_f32_16x16x32_bf16 v[20:23], v[130:133], v[110:113], v[20:23]
	v_mfma_f32_16x16x32_bf16 v[16:19], v[118:121], v[114:117], v[16:19]
	v_mfma_f32_16x16x32_bf16 v[12:15], v[122:125], v[114:117], v[12:15]
	v_mfma_f32_16x16x32_bf16 v[8:11], v[126:129], v[114:117], v[8:11]
	v_mfma_f32_16x16x32_bf16 v[4:7], v[130:133], v[114:117], v[4:7]
	v_mfma_f32_16x16x32_bf16 v[64:67], v[118:121], v[80:83], v[64:67]
	v_mfma_f32_16x16x32_bf16 v[60:63], v[122:125], v[80:83], v[60:63]
	v_mfma_f32_16x16x32_bf16 v[68:71], v[130:133], v[80:83], v[52:55]
	v_mov_b32_e32 v0, v198
	s_waitcnt vmcnt(0) lgkmcnt(0)
	s_barrier
	v_readlane_b32 s4, v252, 35
	v_ashrrev_i32_e32 v2, 1, v0
	v_and_b32_e32 v2, 0xffffffc0, v2
	v_bfe_u32 v80, v0, 4, 2
	v_add_u32_e32 v2, s3, v2
	v_and_b32_e32 v1, 64, v0
	v_and_or_b32 v0, v0, 15, v2
	v_lshlrev_b32_e32 v2, 2, v80
	v_or3_b32 v54, v2, v1, s2
	v_ashrrev_i32_e32 v1, 31, v0
	v_lshlrev_b64 v[52:53], 12, v[0:1]
	v_readlane_b32 s18, v252, 49
	v_readlane_b32 s19, v252, 50
	v_lshlrev_b32_e32 v2, 2, v54
	v_readlane_b32 s5, v252, 36
	v_lshl_add_u64 v[52:53], s[18:19], 0, v[52:53]
	v_lshl_add_u64 v[76:77], v[52:53], 0, v[2:3]
	global_load_dwordx4 v[72:75], v[76:77], off
	v_lshlrev_b32_e32 v52, 1, v54
	v_lshlrev_b64 v[54:55], 11, v[0:1]
	v_mov_b32_e32 v53, v3
	v_lshl_add_u64 v[54:55], s[26:27], 0, v[54:55]
	v_lshl_add_u64 v[78:79], v[54:55], 0, v[52:53]
	v_readlane_b32 s6, v252, 37
	v_readlane_b32 s7, v252, 38
	v_readlane_b32 s8, v252, 39
	v_readlane_b32 s9, v252, 40
	v_readlane_b32 s10, v252, 41
	v_readlane_b32 s11, v252, 42
	v_readlane_b32 s12, v252, 43
	v_readlane_b32 s13, v252, 44
	v_readlane_b32 s14, v252, 45
	v_readlane_b32 s15, v252, 46
	v_readlane_b32 s16, v252, 47
	v_readlane_b32 s17, v252, 48
	s_waitcnt vmcnt(0)
	v_pk_add_f32 v[66:67], v[66:67], v[74:75]
	v_pk_add_f32 v[64:65], v[64:65], v[72:73]
	global_store_dwordx4 v[76:77], v[64:67], off
	v_cvt_pk_bf16_f32 v54, v64, v65
	v_cvt_pk_bf16_f32 v55, v66, v67
	global_store_dwordx2 v[78:79], v[54:55], off
	global_load_dwordx4 v[64:67], v[76:77], off offset:64
	s_waitcnt vmcnt(0)
	v_pk_add_f32 v[62:63], v[62:63], v[66:67]
	v_pk_add_f32 v[60:61], v[60:61], v[64:65]
	global_store_dwordx4 v[76:77], v[60:63], off offset:64
	v_cvt_pk_bf16_f32 v64, v60, v61
	v_cvt_pk_bf16_f32 v65, v62, v63
	global_store_dwordx2 v[78:79], v[64:65], off offset:32
	global_load_dwordx4 v[60:63], v[76:77], off offset:128
	v_lshlrev_b32_e32 v66, 16, v54
	v_and_b32_e32 v54, 0xffff0000, v54
	v_mul_f32_e32 v54, v54, v54
	v_lshlrev_b32_e32 v67, 16, v55
	v_fmac_f32_e32 v54, v66, v66
	v_and_b32_e32 v55, 0xffff0000, v55
	v_fmac_f32_e32 v54, v67, v67
	v_fmac_f32_e32 v54, v55, v55
	v_lshlrev_b32_e32 v55, 16, v64
	v_and_b32_e32 v64, 0xffff0000, v64
	v_mul_f32_e32 v64, v64, v64
	v_lshlrev_b32_e32 v66, 16, v65
	v_fmac_f32_e32 v64, v55, v55
	v_and_b32_e32 v65, 0xffff0000, v65
	v_fmac_f32_e32 v64, v66, v66
	v_fmac_f32_e32 v64, v65, v65
	v_add_f32_e32 v54, v54, v64
	s_waitcnt vmcnt(0)
	v_pk_add_f32 v[58:59], v[58:59], v[62:63]
	v_pk_add_f32 v[56:57], v[56:57], v[60:61]
	global_store_dwordx4 v[76:77], v[56:59], off offset:128
	v_cvt_pk_bf16_f32 v62, v56, v57
	v_cvt_pk_bf16_f32 v63, v58, v59
	global_store_dwordx2 v[78:79], v[62:63], off offset:64
	global_load_dwordx4 v[58:61], v[76:77], off offset:192
	v_lshlrev_b32_e32 v55, 16, v62
	v_and_b32_e32 v62, 0xffff0000, v62
	v_mul_f32_e32 v62, v62, v62
	v_lshlrev_b32_e32 v64, 16, v63
	v_fmac_f32_e32 v62, v55, v55
	v_and_b32_e32 v63, 0xffff0000, v63
	v_fmac_f32_e32 v62, v64, v64
	v_fmac_f32_e32 v62, v63, v63
	v_add_f32_e32 v54, v54, v62
	v_and_b32_e32 v57, 64, v218
	v_xor_b32_e32 v56, 16, v218
	v_add_u32_e32 v57, 64, v57
	v_cmp_lt_i32_e32 vcc, v56, v57
	s_waitcnt vmcnt(0)
	v_pk_add_f32 v[58:59], v[68:69], v[58:59]
	s_nop 0
	v_cvt_pk_bf16_f32 v62, v58, v59
	v_pk_add_f32 v[60:61], v[70:71], v[60:61]
	v_and_b32_e32 v64, 0xffff0000, v62
	v_lshlrev_b32_e32 v55, 16, v62
	v_mul_f32_e32 v64, v64, v64
	v_cvt_pk_bf16_f32 v63, v60, v61
	v_fmac_f32_e32 v64, v55, v55
	v_lshlrev_b32_e32 v65, 16, v63
	v_and_b32_e32 v66, 0xffff0000, v63
	v_fmac_f32_e32 v64, v65, v65
	v_cndmask_b32_e32 v56, v218, v56, vcc
	v_fmac_f32_e32 v64, v66, v66
	v_lshlrev_b32_e32 v56, 2, v56
	v_add_f32_e32 v54, v54, v64
	ds_bpermute_b32 v55, v56, v54
	v_xor_b32_e32 v64, 32, v218
	v_cmp_lt_i32_e32 vcc, v64, v57
	global_store_dwordx4 v[76:77], v[58:61], off offset:192
	global_store_dwordx2 v[78:79], v[62:63], off offset:96
	v_cndmask_b32_e32 v57, v218, v64, vcc
	s_waitcnt lgkmcnt(0)
	v_add_f32_e32 v54, v54, v55
	v_lshlrev_b32_e32 v57, 2, v57
	ds_bpermute_b32 v55, v57, v54
	v_cmp_eq_u32_e32 vcc, 0, v80
	s_and_saveexec_b64 s[28:29], vcc
	s_cbranch_execz .LBB0_98
	v_lshl_add_u64 v[58:59], v[0:1], 2, s[24:25]
	s_waitcnt lgkmcnt(0)
	v_add_f32_e32 v1, v54, v55
	global_atomic_add_f32 v[58:59], v1, off

; __device__ __forceinline__ unsigned char* WS(const Params& p) { unsigned z = 0; asm volatile("" : "+s"(z)); return p.ws + z; }
; __device__ __forceinline__ void gemm_mainloop_d(const bf16_t* __restrict__ Ap, int lda, const bf16_t* __restrict__ Bt, int K,
;                                                 int m0, int n0, f32x4 (&acc)[4][4], char* lds) {
;     ...
;   auto dma = [&](int kt, int st) {
;     char* la = lds + st * 32768; char* lb = la + 16384;
; #pragma unroll
;     for (int i = 0; i < 4; i++) {
;       const int row = i * 32 + lrow; const int c = cph ^ ((row >> 1) & 7);
;       __builtin_amdgcn_global_load_lds((const unsigned*)(Ap + (size_t)(m0 + row) * lda + kt * 64 + c * 8), (__attribute__((address_space(3))) unsigned*)(la + i * 4096 + tid * 16), 16, 0, 0);
;       __builtin_amdgcn_global_load_lds((const unsigned*)(Bt + (size_t)(n0 + row) * K + kt * 64 + c * 8), (__attribute__((address_space(3))) unsigned*)(lb + i * 4096 + tid * 16), 16, 0, 0);
;     }
;   };
;   dma(0, 0);
;   asm volatile("s_waitcnt vmcnt(0)" ::: "memory"); __builtin_amdgcn_s_barrier(); asm volatile("" ::: "memory");
; __device__ __forceinline__ void gemm_GU(const Params& p, int item, char* lds) {
;   const int r_ = item >> 9, x_ = item & 7, y_ = (item >> 3) & 63;
;   const int pid = (r_ * 8 + x_) * 2 + (y_ >> 5), t32 = y_ & 31;
;   const int mt = (pid / 11) * 8 + (t32 >> 2), nt = (pid % 11) * 4 + (t32 & 3); const int m0 = mt * 128, n0 = nt * 128;
;   f32x4 acc[4][4];
;   gemm_mainloop_d((const bf16_t*)(WS(p) + OFF_XB), DM, (const bf16_t*)(WS(p) + OFF_WGU), DM, m0, n0, acc, lds);
.LBB0_105:
	s_andn2_b64 vcc, exec, s[24:25]
	s_cbranch_vccnz .LBB0_111
	v_readlane_b32 s2, v254, 7
	v_readlane_b32 s3, v254, 8
	s_andn2_b64 vcc, exec, s[2:3]
	s_cbranch_vccnz .LBB0_111
	s_waitcnt lgkmcnt(0)
	s_lshl_b32 s2, s77, 2
	s_lshl_b32 s3, s77, 4
	v_readlane_b32 s28, v254, 58
	v_readlane_b32 s29, v254, 46
	v_readlane_b32 s30, v252, 0
	v_readlane_b32 vcc_lo, v252, 0
	s_nop 0
	s_cmpk_lt_u32 vcc_lo, 0x100
	s_cbranch_scc0 .Lmy_sp_e
	s_setprio 1
.Lmy_sp_e:
.LBB0_108:
	s_ashr_i32 s25, s30, 6
	s_and_b32 s24, s30, 7
	s_and_b32 s25, s25, 0x7ffffff8
	s_or_b32 s24, s25, s24
	s_lshl_b32 s24, s24, 1
	s_bfe_u32 s25, s30, 0x10008
	s_or_b32 s38, s24, s25
	s_mul_hi_i32 s24, s38, 0x2e8ba2e9
	s_lshr_b32 s25, s24, 31
	s_ashr_i32 s24, s24, 1
	s_add_i32 s39, s24, s25
	s_mul_i32 s24, s39, 11
	s_sub_i32 s25, s38, s24
	s_lshl_b32 s24, s30, 2
	s_lshl_b32 s26, s30, 4
	s_lshl_b32 s40, s39, 10
	s_and_b32 s24, s24, 0x380
	s_lshl_b32 s25, s25, 9
	s_and_b32 s26, s26, 0x180
	s_and_b32 s36, s29, 0x380
	s_and_b32 s37, s28, 0x180
	s_or_b32 s24, s40, s24
	s_or_b32 s31, s25, s26
	s_mov_b32 s41, 0
	s_mov_b32 s42, 0
	s_waitcnt vmcnt(5)
	v_mov_b32_e32 v4, v198
	s_add_u32 s26, s46, s41
	s_addc_u32 s27, s47, 0
	v_ashrrev_i32_e32 v7, 3, v4
	v_lshrrev_b32_e32 v8, 1, v7
	s_waitcnt vmcnt(4)
	v_add_u32_e32 v0, s24, v7
	s_add_u32 s34, s26, 0x65a8000
	v_xor_b32_e32 v2, v8, v4
	v_ashrrev_i32_e32 v1, 31, v0
	s_addc_u32 s35, s27, 0
	v_lshlrev_b64 v[0:1], 11, v[0:1]
	v_lshlrev_b32_e32 v2, 4, v2
	v_lshl_add_u32 v82, v4, 4, 0
	v_lshl_add_u64 v[0:1], s[34:35], 0, v[0:1]
	v_and_b32_e32 v2, 0x70, v2
	v_readfirstlane_b32 s43, v82
	s_add_u32 s26, s46, s42
	v_lshl_add_u64 v[0:1], v[0:1], 0, v[2:3]
	s_mov_b32 m0, s43
	s_addc_u32 s27, s47, 0
	global_load_lds_dwordx4 v[0:1], off
	v_add_u32_e32 v0, s31, v7
	s_add_u32 s26, s26, 0xe8cc000
	v_ashrrev_i32_e32 v1, 31, v0
	s_addc_u32 s27, s27, 0
	v_lshlrev_b64 v[0:1], 11, v[0:1]
	v_add_u32_e32 v9, 0x4000, v82
	v_lshl_add_u64 v[0:1], s[26:27], 0, v[0:1]
	v_readfirstlane_b32 s43, v9
	v_lshl_add_u64 v[0:1], v[0:1], 0, v[2:3]
	s_mov_b32 m0, s43
	v_add_u32_e32 v9, 32, v7
	global_load_lds_dwordx4 v[0:1], off
	v_add_u32_e32 v0, s24, v9
	v_ashrrev_i32_e32 v1, 31, v0
	v_lshlrev_b64 v[0:1], 11, v[0:1]
	v_add_u32_e32 v10, 0x1000, v82
	v_lshl_add_u64 v[0:1], s[34:35], 0, v[0:1]
	v_readfirstlane_b32 s43, v10
	v_lshl_add_u64 v[0:1], v[0:1], 0, v[2:3]
	s_mov_b32 m0, s43
	v_add_u32_e32 v10, 0x5000, v82
	global_load_lds_dwordx4 v[0:1], off
	v_add_u32_e32 v0, s31, v9
	v_ashrrev_i32_e32 v1, 31, v0
	v_lshlrev_b64 v[0:1], 11, v[0:1]
	v_lshl_add_u64 v[0:1], s[26:27], 0, v[0:1]
	v_readfirstlane_b32 s43, v10
	v_lshl_add_u64 v[0:1], v[0:1], 0, v[2:3]
	s_mov_b32 m0, s43
	v_add_u32_e32 v10, 64, v7
	global_load_lds_dwordx4 v[0:1], off
	v_add_u32_e32 v0, s24, v10
	v_ashrrev_i32_e32 v1, 31, v0
	v_lshlrev_b64 v[0:1], 11, v[0:1]
	v_add_u32_e32 v11, 0x2000, v82
	v_lshl_add_u64 v[0:1], s[34:35], 0, v[0:1]
	v_readfirstlane_b32 s43, v11
	v_lshl_add_u64 v[0:1], v[0:1], 0, v[2:3]
	s_mov_b32 m0, s43
	v_add_u32_e32 v11, 0x6000, v82
	global_load_lds_dwordx4 v[0:1], off
	v_add_u32_e32 v0, s31, v10
	v_ashrrev_i32_e32 v1, 31, v0
	v_lshlrev_b64 v[0:1], 11, v[0:1]
	v_lshl_add_u64 v[0:1], s[26:27], 0, v[0:1]
	v_readfirstlane_b32 s43, v11
	v_lshl_add_u64 v[0:1], v[0:1], 0, v[2:3]
	s_mov_b32 m0, s43
	v_add_u32_e32 v11, 0x60, v7
	global_load_lds_dwordx4 v[0:1], off
	v_add_u32_e32 v0, s24, v11
	v_ashrrev_i32_e32 v1, 31, v0
	v_lshlrev_b64 v[0:1], 11, v[0:1]
	v_add_u32_e32 v12, 0x3000, v82
	v_lshl_add_u64 v[0:1], s[34:35], 0, v[0:1]
	v_readfirstlane_b32 s34, v12
	v_lshl_add_u64 v[0:1], v[0:1], 0, v[2:3]
	s_mov_b32 m0, s34
	s_mov_b32 s4, 0x1ffffc0
	global_load_lds_dwordx4 v[0:1], off
	v_add_u32_e32 v0, s31, v11
	v_ashrrev_i32_e32 v1, 31, v0
	v_lshlrev_b64 v[0:1], 11, v[0:1]
	v_lshl_add_u64 v[0:1], s[26:27], 0, v[0:1]
	v_lshl_add_u64 v[0:1], v[0:1], 0, v[2:3]
	v_add_u32_e32 v2, 0x7000, v82
	s_or_b32 s36, s36, s40
	v_readfirstlane_b32 s26, v2
	s_mov_b32 m0, s26
	v_lshrrev_b32_e32 v5, 4, v4
	global_load_lds_dwordx4 v[0:1], off
	v_and_b32_e32 v0, 15, v4
	v_lshrrev_b32_e32 v1, 1, v4
	v_and_or_b32 v0, v1, s4, v0
	v_readlane_b32 s4, v254, 44
	s_add_u32 s26, s4, s41
	v_readlane_b32 s4, v254, 45
	s_addc_u32 s27, s4, 0
	s_lshl_b32 s34, s38, 9
	v_bfe_u32 v6, v4, 4, 2
	v_bfe_u32 v1, v4, 1, 3
	v_lshlrev_b32_e32 v2, 7, v4
	v_bitop3_b32 v4, v8, 7, v4 bitop3:0x48
	s_or_b32 s37, s37, s34
	v_bitop3_b32 v5, v5, v1, 3 bitop3:0x6c
	v_bitop3_b32 v1, v6, v1, 4 bitop3:0x36
	v_lshlrev_b32_e32 v6, 4, v4
	v_add_u32_e32 v4, s37, v7
	s_mulk_i32 s39, 0x1600
	v_and_b32_e32 v2, 0x2780, v2
	v_lshlrev_b32_e32 v5, 4, v5
	v_lshlrev_b32_e32 v0, 7, v0
	v_subrev_u32_e32 v4, s39, v4
	v_or_b32_e32 v85, v0, v5
	v_or_b32_e32 v84, v5, v2
	v_ashrrev_i32_e32 v5, 31, v4
	v_readlane_b32 s4, v254, 47
	v_lshlrev_b64 v[4:5], 11, v[4:5]
	s_add_u32 s34, s4, s42
	v_readlane_b32 s4, v254, 48
	v_or_b32_e32 v4, v4, v6
	s_addc_u32 s35, s4, 0
	s_waitcnt vmcnt(0)
	v_lshl_add_u64 v[68:69], s[34:35], 0, v[4:5]
	v_add_u32_e32 v4, s36, v9
	v_ashrrev_i32_e32 v5, 31, v4
	v_lshlrev_b64 v[4:5], 11, v[4:5]
	v_or_b32_e32 v4, v4, v6
	v_lshl_add_u64 v[70:71], s[26:27], 0, v[4:5]
	v_add_u32_e32 v4, s37, v9
	v_subrev_u32_e32 v4, s39, v4
	v_ashrrev_i32_e32 v5, 31, v4
	v_lshlrev_b64 v[4:5], 11, v[4:5]
	v_or_b32_e32 v4, v4, v6
	v_lshl_add_u64 v[72:73], s[34:35], 0, v[4:5]
	v_add_u32_e32 v4, s36, v10
	v_ashrrev_i32_e32 v5, 31, v4
	v_lshlrev_b64 v[4:5], 11, v[4:5]
	v_or_b32_e32 v4, v4, v6
	v_lshl_add_u64 v[74:75], s[26:27], 0, v[4:5]
	v_add_u32_e32 v4, s37, v10
	v_subrev_u32_e32 v4, s39, v4
	v_ashrrev_i32_e32 v5, 31, v4
	v_lshlrev_b64 v[4:5], 11, v[4:5]
	v_or_b32_e32 v4, v4, v6
	v_lshl_add_u64 v[76:77], s[34:35], 0, v[4:5]
	v_add_u32_e32 v4, s36, v11
	v_ashrrev_i32_e32 v5, 31, v4
	v_lshlrev_b64 v[4:5], 11, v[4:5]
	v_or_b32_e32 v4, v4, v6
	v_lshl_add_u64 v[78:79], s[26:27], 0, v[4:5]
	v_add_u32_e32 v4, s37, v11
	v_lshlrev_b32_e32 v1, 4, v1
	v_subrev_u32_e32 v4, s39, v4
	v_or_b32_e32 v83, v1, v0
	v_add_u32_e32 v0, s36, v7
	v_ashrrev_i32_e32 v5, 31, v4
	v_or_b32_e32 v2, v1, v2
	v_ashrrev_i32_e32 v1, 31, v0
	v_lshlrev_b64 v[4:5], 11, v[4:5]
	s_waitcnt vmcnt(0)
	s_barrier
; __device__ __forceinline__ void gemm_mainloop_d(const bf16_t* __restrict__ Ap, int lda, const bf16_t* __restrict__ Bt, int K,
;                                                 int m0, int n0, f32x4 (&acc)[4][4], char* lds) {
;     ...
; #pragma unroll
;   for (int m = 0; m < 4; m++)
; #pragma unroll
;     for (int n = 0; n < 4; n++) acc[m][n] = (f32x4){0.f, 0.f, 0.f, 0.f};
;     ...
;   for (int kt = 0; kt < nk; kt++) {
;     const int st = kt & 1;
;     if (kt + 1 < nk) dma(kt + 1, st ^ 1);
;     const char* la = lds + st * 32768; const char* lb = la + 16384;
;     bf16x8 af[2][4], bfv[2][4];
; #pragma unroll
;     for (int kc = 0; kc < 2; kc++) {
; #pragma unroll
;       for (int m = 0; m < 4; m++) { const int row = wr * 64 + m * 16 + fr; af[kc][m] = *(const bf16x8*)(la + (row * 8 + ((kc * 4 + fq) ^ ((row >> 1) & 7))) * 16); }
; #pragma unroll
;       for (int n = 0; n < 4; n++) { const int row = wc * 64 + n * 16 + fr; bfv[kc][n] = *(const bf16x8*)(lb + (row * 8 + ((kc * 4 + fq) ^ ((row >> 1) & 7))) * 16); }
;     }
;     __builtin_amdgcn_s_setprio(1);
; #pragma unroll
;     for (int kc = 0; kc < 2; kc++)
; #pragma unroll
;       for (int m = 0; m < 4; m++)
; #pragma unroll
;         for (int n = 0; n < 4; n++) acc[m][n] = __builtin_amdgcn_mfma_f32_16x16x32_bf16(bfv[kc][n], af[kc][m], acc[m][n], 0, 0, 0);
;     __builtin_amdgcn_s_setprio(0);
;     asm volatile("s_waitcnt vmcnt(0) lgkmcnt(0)" ::: "memory"); __builtin_amdgcn_s_barrier(); asm volatile("" ::: "memory");
	v_lshlrev_b64 v[0:1], 11, v[0:1]
	v_or_b32_e32 v4, v4, v6
	v_or_b32_e32 v0, v0, v6
	v_lshl_add_u64 v[80:81], s[34:35], 0, v[4:5]
	v_mov_b32_e32 v4, 0
	s_mov_b32 s25, 0
	v_lshl_add_u64 v[0:1], s[26:27], 0, v[0:1]
	s_mov_b64 s[26:27], 0
	v_mov_b32_e32 v5, v4
	v_mov_b32_e32 v6, v4
	v_mov_b32_e32 v7, v4
	v_mov_b32_e32 v8, v4
	v_mov_b32_e32 v9, v4
	v_mov_b32_e32 v10, v4
	v_mov_b32_e32 v11, v4
	v_mov_b32_e32 v12, v4
	v_mov_b32_e32 v13, v4
	v_mov_b32_e32 v14, v4
	v_mov_b32_e32 v15, v4
	v_mov_b32_e32 v16, v4
	v_mov_b32_e32 v17, v4
	v_mov_b32_e32 v18, v4
	v_mov_b32_e32 v19, v4
	v_mov_b32_e32 v20, v4
	v_mov_b32_e32 v21, v4
	v_mov_b32_e32 v22, v4
	v_mov_b32_e32 v23, v4
	v_mov_b32_e32 v24, v4
	v_mov_b32_e32 v25, v4
	v_mov_b32_e32 v26, v4
	v_mov_b32_e32 v27, v4
	v_mov_b32_e32 v28, v4
	v_mov_b32_e32 v29, v4
	v_mov_b32_e32 v30, v4
	v_mov_b32_e32 v31, v4
	v_mov_b32_e32 v32, v4
	v_mov_b32_e32 v33, v4
	v_mov_b32_e32 v34, v4
	v_mov_b32_e32 v35, v4
	v_mov_b32_e32 v36, v4
	v_mov_b32_e32 v37, v4
	v_mov_b32_e32 v38, v4
	v_mov_b32_e32 v39, v4
	v_mov_b32_e32 v40, v4
	v_mov_b32_e32 v41, v4
	v_mov_b32_e32 v42, v4
	v_mov_b32_e32 v43, v4
	v_mov_b32_e32 v44, v4
	v_mov_b32_e32 v45, v4
	v_mov_b32_e32 v46, v4
	v_mov_b32_e32 v47, v4
	v_mov_b32_e32 v48, v4
	v_mov_b32_e32 v49, v4
	v_mov_b32_e32 v50, v4
	v_mov_b32_e32 v51, v4
	v_mov_b32_e32 v52, v4
	v_mov_b32_e32 v53, v4
	v_mov_b32_e32 v54, v4
	v_mov_b32_e32 v55, v4
	v_mov_b32_e32 v56, v4
	v_mov_b32_e32 v57, v4
	v_mov_b32_e32 v58, v4
	v_mov_b32_e32 v59, v4
	v_mov_b32_e32 v60, v4
	v_mov_b32_e32 v61, v4
	v_mov_b32_e32 v62, v4
	v_mov_b32_e32 v63, v4
	v_mov_b32_e32 v64, v4
	v_mov_b32_e32 v65, v4
	v_mov_b32_e32 v66, v4
	v_mov_b32_e32 v67, v4
	v_subrev_u32_e32 v150, s46, v0
	v_subrev_u32_e32 v151, s46, v68
	v_subrev_u32_e32 v152, s46, v70
	v_subrev_u32_e32 v153, s46, v72
	v_subrev_u32_e32 v154, s46, v74
	v_subrev_u32_e32 v155, s46, v76
	v_subrev_u32_e32 v156, s46, v78
	v_subrev_u32_e32 v157, s46, v80
	v_readfirstlane_b32 vcc_hi, v82
.LBB0_109:
	s_and_b32 s34, s25, 0x8000
	s_xor_b32 s35, s34, 0x8000
	s_add_i32 s35, s35, vcc_hi
	s_mov_b32 m0, s35
	s_add_i32 vcc_lo, s35, 0x4000
	global_load_lds_dwordx4 v150, s[46:47]
	s_mov_b32 m0, vcc_lo
	s_add_i32 vcc_lo, s35, 0x1000
	global_load_lds_dwordx4 v151, s[46:47]
	s_mov_b32 m0, vcc_lo
	s_add_i32 vcc_lo, s35, 0x5000
	global_load_lds_dwordx4 v152, s[46:47]
	s_mov_b32 m0, vcc_lo
	s_add_i32 vcc_lo, s35, 0x2000
	global_load_lds_dwordx4 v153, s[46:47]
	s_mov_b32 m0, vcc_lo
	s_add_i32 vcc_lo, s35, 0x6000
	global_load_lds_dwordx4 v154, s[46:47]
	s_mov_b32 m0, vcc_lo
	s_add_i32 vcc_lo, s35, 0x3000
	global_load_lds_dwordx4 v155, s[46:47]
	s_mov_b32 m0, vcc_lo
	s_add_i32 vcc_lo, s35, 0x7000
	global_load_lds_dwordx4 v156, s[46:47]
	s_mov_b32 m0, vcc_lo
	s_nop 0
	global_load_lds_dwordx4 v157, s[46:47]
	v_add_u32_e32 v150, 0x80, v150
	v_add_u32_e32 v151, 0x80, v151
	v_add_u32_e32 v152, 0x80, v152
	v_add_u32_e32 v153, 0x80, v153
	v_add_u32_e32 v154, 0x80, v154
	v_add_u32_e32 v155, 0x80, v155
	v_add_u32_e32 v156, 0x80, v156
	v_add_u32_e32 v157, 0x80, v157
	v_add_u32_e32 v98, s34, v85
	v_add_u32_e32 v114, s34, v84
	v_add_u32_e32 v130, s34, v83
	v_add_u32_e32 v146, s34, v2
	ds_read_b128 v[86:89], v98
	ds_read_b128 v[90:93], v98 offset:2048
	ds_read_b128 v[94:97], v98 offset:4096
	ds_read_b128 v[98:101], v98 offset:6144
	ds_read_b128 v[102:105], v114 offset:16384
	ds_read_b128 v[106:109], v114 offset:18432
	ds_read_b128 v[110:113], v114 offset:20480
	ds_read_b128 v[114:117], v114 offset:22528
	ds_read_b128 v[118:121], v130
	ds_read_b128 v[122:125], v130 offset:2048
	ds_read_b128 v[126:129], v130 offset:4096
	ds_read_b128 v[130:133], v130 offset:6144
	ds_read_b128 v[134:137], v146 offset:16384
	ds_read_b128 v[138:141], v146 offset:18432
	ds_read_b128 v[142:145], v146 offset:20480
	ds_read_b128 v[146:149], v146 offset:22528
	s_waitcnt lgkmcnt(0)
	v_mfma_f32_16x16x32_bf16 v[64:67], v[102:105], v[86:89], v[64:67]
	v_mfma_f32_16x16x32_bf16 v[60:63], v[106:109], v[86:89], v[60:63]
	v_mfma_f32_16x16x32_bf16 v[56:59], v[110:113], v[86:89], v[56:59]
	v_mfma_f32_16x16x32_bf16 v[52:55], v[114:117], v[86:89], v[52:55]
	v_mfma_f32_16x16x32_bf16 v[48:51], v[102:105], v[90:93], v[48:51]
	v_mfma_f32_16x16x32_bf16 v[44:47], v[106:109], v[90:93], v[44:47]
	v_mfma_f32_16x16x32_bf16 v[40:43], v[110:113], v[90:93], v[40:43]
	v_mfma_f32_16x16x32_bf16 v[36:39], v[114:117], v[90:93], v[36:39]
	v_mfma_f32_16x16x32_bf16 v[32:35], v[102:105], v[94:97], v[32:35]
	v_mfma_f32_16x16x32_bf16 v[28:31], v[106:109], v[94:97], v[28:31]
	v_mfma_f32_16x16x32_bf16 v[24:27], v[110:113], v[94:97], v[24:27]
	v_mfma_f32_16x16x32_bf16 v[20:23], v[114:117], v[94:97], v[20:23]
	v_mfma_f32_16x16x32_bf16 v[16:19], v[102:105], v[98:101], v[16:19]
	v_mfma_f32_16x16x32_bf16 v[12:15], v[106:109], v[98:101], v[12:15]
	v_mfma_f32_16x16x32_bf16 v[8:11], v[110:113], v[98:101], v[8:11]
	v_mfma_f32_16x16x32_bf16 v[4:7], v[114:117], v[98:101], v[4:7]
	v_mfma_f32_16x16x32_bf16 v[64:67], v[134:137], v[118:121], v[64:67]
	v_mfma_f32_16x16x32_bf16 v[60:63], v[138:141], v[118:121], v[60:63]
	v_mfma_f32_16x16x32_bf16 v[56:59], v[142:145], v[118:121], v[56:59]
	v_mfma_f32_16x16x32_bf16 v[52:55], v[146:149], v[118:121], v[52:55]
	v_mfma_f32_16x16x32_bf16 v[48:51], v[134:137], v[122:125], v[48:51]
	v_mfma_f32_16x16x32_bf16 v[44:47], v[138:141], v[122:125], v[44:47]
	v_mfma_f32_16x16x32_bf16 v[40:43], v[142:145], v[122:125], v[40:43]
	v_mfma_f32_16x16x32_bf16 v[36:39], v[146:149], v[122:125], v[36:39]
	v_mfma_f32_16x16x32_bf16 v[32:35], v[134:137], v[126:129], v[32:35]
	v_mfma_f32_16x16x32_bf16 v[28:31], v[138:141], v[126:129], v[28:31]
	v_mfma_f32_16x16x32_bf16 v[24:27], v[142:145], v[126:129], v[24:27]
	v_mfma_f32_16x16x32_bf16 v[20:23], v[146:149], v[126:129], v[20:23]
	v_mfma_f32_16x16x32_bf16 v[16:19], v[134:137], v[130:133], v[16:19]
	v_mfma_f32_16x16x32_bf16 v[12:15], v[138:141], v[130:133], v[12:15]
	v_mfma_f32_16x16x32_bf16 v[8:11], v[142:145], v[130:133], v[8:11]
	v_mfma_f32_16x16x32_bf16 v[4:7], v[146:149], v[130:133], v[4:7]
	s_waitcnt vmcnt(0) lgkmcnt(0)
	s_barrier
; __device__ __forceinline__ unsigned char* WS(const Params& p) { unsigned z = 0; asm volatile("" : "+s"(z)); return p.ws + z; }
; __device__ __forceinline__ void gemm_mainloop_d(const bf16_t* __restrict__ Ap, int lda, const bf16_t* __restrict__ Bt, int K,
;                                                 int m0, int n0, f32x4 (&acc)[4][4], char* lds) {
;     ...
;   for (int kt = 0; kt < nk; kt++) {
;     const int st = kt & 1;
;     if (kt + 1 < nk) dma(kt + 1, st ^ 1);
;     const char* la = lds + st * 32768; const char* lb = la + 16384;
;     bf16x8 af[2][4], bfv[2][4];
; #pragma unroll
;     for (int kc = 0; kc < 2; kc++) {
; #pragma unroll
;       for (int m = 0; m < 4; m++) { const int row = wr * 64 + m * 16 + fr; af[kc][m] = *(const bf16x8*)(la + (row * 8 + ((kc * 4 + fq) ^ ((row >> 1) & 7))) * 16); }
; #pragma unroll
;       for (int n = 0; n < 4; n++) { const int row = wc * 64 + n * 16 + fr; bfv[kc][n] = *(const bf16x8*)(lb + (row * 8 + ((kc * 4 + fq) ^ ((row >> 1) & 7))) * 16); }
;     }
;     __builtin_amdgcn_s_setprio(1);
; #pragma unroll
;     for (int kc = 0; kc < 2; kc++)
; #pragma unroll
;       for (int m = 0; m < 4; m++)
; #pragma unroll
;         for (int n = 0; n < 4; n++) acc[m][n] = __builtin_amdgcn_mfma_f32_16x16x32_bf16(bfv[kc][n], af[kc][m], acc[m][n], 0, 0, 0);
;     __builtin_amdgcn_s_setprio(0);
;     asm volatile("s_waitcnt vmcnt(0) lgkmcnt(0)" ::: "memory"); __builtin_amdgcn_s_barrier(); asm volatile("" ::: "memory");
; __device__ __forceinline__ void gemm_GU(const Params& p, int item, char* lds) {
;     ...
;   const float* rssg = (const float*)(WS(p) + OFF_RSS) + T + m0;
;   bf16_t* U = (bf16_t*)(WS(p) + OFF_U);
; #pragma unroll
;   for (int m = 0; m < 4; m++) {
;     const int rl = wr * 64 + m * 16 + fr; const float r = rsqrtf(rssg[rl] * (1.f / 1024.f) + 1e-6f);
	s_add_u32 s26, s26, 0x80
	s_addc_u32 s27, s27, 0
	s_add_i32 s25, s25, 0x8000
	s_cmpk_lg_i32 s26, 0x780
	s_cbranch_scc1 .LBB0_109
	v_add_u32_e32 v0, 0, v85
	ds_read_b128 v[68:71], v0 offset:32768
	ds_read_b128 v[72:75], v0 offset:34816
	ds_read_b128 v[76:79], v0 offset:36864
	ds_read_b128 v[86:89], v0 offset:38912
	v_add_u32_e32 v0, 0, v84
	ds_read_b128 v[90:93], v0 offset:49152
	ds_read_b128 v[94:97], v0 offset:51200
	ds_read_b128 v[98:101], v0 offset:53248
	ds_read_b128 v[102:105], v0 offset:55296
	v_add_u32_e32 v0, 0, v83
	ds_read_b128 v[80:83], v0 offset:32768
	ds_read_b128 v[106:109], v0 offset:34816
	ds_read_b128 v[110:113], v0 offset:36864
	ds_read_b128 v[114:117], v0 offset:38912
	v_add_u32_e32 v0, 0, v2
	ds_read_b128 v[118:121], v0 offset:49152
	ds_read_b128 v[122:125], v0 offset:51200
	ds_read_b128 v[126:129], v0 offset:53248
	ds_read_b128 v[130:133], v0 offset:55296
	s_waitcnt lgkmcnt(0)
	v_mfma_f32_16x16x32_bf16 v[64:67], v[90:93], v[68:71], v[64:67]
	v_mfma_f32_16x16x32_bf16 v[60:63], v[94:97], v[68:71], v[60:63]
	v_mfma_f32_16x16x32_bf16 v[56:59], v[98:101], v[68:71], v[56:59]
	v_mfma_f32_16x16x32_bf16 v[52:55], v[102:105], v[68:71], v[52:55]
	v_mfma_f32_16x16x32_bf16 v[48:51], v[90:93], v[72:75], v[48:51]
	v_mfma_f32_16x16x32_bf16 v[44:47], v[94:97], v[72:75], v[44:47]
	v_mfma_f32_16x16x32_bf16 v[68:71], v[98:101], v[72:75], v[40:43]
	v_mfma_f32_16x16x32_bf16 v[72:75], v[102:105], v[72:75], v[36:39]
	v_mfma_f32_16x16x32_bf16 v[32:35], v[90:93], v[76:79], v[32:35]
	v_mfma_f32_16x16x32_bf16 v[28:31], v[94:97], v[76:79], v[28:31]
	v_mfma_f32_16x16x32_bf16 v[134:137], v[98:101], v[76:79], v[24:27]
	v_mfma_f32_16x16x32_bf16 v[76:79], v[102:105], v[76:79], v[20:23]
	v_mfma_f32_16x16x32_bf16 v[16:19], v[90:93], v[86:89], v[16:19]
	v_mfma_f32_16x16x32_bf16 v[12:15], v[94:97], v[86:89], v[12:15]
	v_mfma_f32_16x16x32_bf16 v[90:93], v[98:101], v[86:89], v[8:11]
	v_mfma_f32_16x16x32_bf16 v[84:87], v[102:105], v[86:89], v[4:7]
	v_mfma_f32_16x16x32_bf16 v[64:67], v[118:121], v[80:83], v[64:67]
	v_mfma_f32_16x16x32_bf16 v[60:63], v[122:125], v[80:83], v[60:63]
	v_mfma_f32_16x16x32_bf16 v[56:59], v[126:129], v[80:83], v[56:59]
	v_mfma_f32_16x16x32_bf16 v[52:55], v[130:133], v[80:83], v[52:55]
	v_mfma_f32_16x16x32_bf16 v[40:43], v[118:121], v[106:109], v[48:51]
	v_mfma_f32_16x16x32_bf16 v[48:51], v[122:125], v[106:109], v[44:47]
	v_mfma_f32_16x16x32_bf16 v[36:39], v[126:129], v[106:109], v[68:71]
	v_mfma_f32_16x16x32_bf16 v[44:47], v[130:133], v[106:109], v[72:75]
	v_mfma_f32_16x16x32_bf16 v[24:27], v[118:121], v[110:113], v[32:35]
	v_mfma_f32_16x16x32_bf16 v[32:35], v[122:125], v[110:113], v[28:31]
	v_mfma_f32_16x16x32_bf16 v[20:23], v[126:129], v[110:113], v[134:137]
	v_mfma_f32_16x16x32_bf16 v[28:31], v[130:133], v[110:113], v[76:79]
	v_mfma_f32_16x16x32_bf16 v[8:11], v[118:121], v[114:117], v[16:19]
	v_mfma_f32_16x16x32_bf16 v[16:19], v[122:125], v[114:117], v[12:15]
	v_mfma_f32_16x16x32_bf16 v[4:7], v[126:129], v[114:117], v[90:93]
	v_mfma_f32_16x16x32_bf16 v[12:15], v[130:133], v[114:117], v[84:87]
	v_mov_b32_e32 v2, v198
	s_mov_b32 s25, s89
	s_waitcnt vmcnt(0) lgkmcnt(0)
	s_barrier
	s_add_u32 s34, s46, s25
	s_addc_u32 s35, s47, 0
	s_ashr_i32 s25, s24, 31
	v_and_b32_e32 v0, 15, v2
	s_lshl_b64 s[26:27], s[24:25], 2
	v_ashrrev_i32_e32 v1, 1, v2
	s_movk_i32 s4, 0xffc0
	s_add_u32 s26, s34, s26
	v_and_or_b32 v0, v1, s4, v0
	s_addc_u32 s27, s35, s27
	v_ashrrev_i32_e32 v1, 31, v0
	v_lshl_add_u64 v[68:69], v[0:1], 2, s[26:27]
	s_mov_b32 s26, 0xff9c000
	v_add_co_u32_e32 v70, vcc, s26, v68
	s_mov_b32 s25, s89
	s_nop 0
	v_addc_co_u32_e32 v71, vcc, 0, v69, vcc
	global_load_dword v74, v[70:71], off
	v_mov_b32_e32 v71, v64
	v_mov_b32_e32 v64, v61
	v_mov_b32_e32 v61, v66
	v_mov_b32_e32 v66, v63
	v_mov_b32_e32 v63, v56
	v_mov_b32_e32 v56, v53
	v_mov_b32_e32 v70, v60
	v_mov_b32_e32 v60, v62
	v_mov_b32_e32 v62, v52
	v_mov_b32_e32 v72, v54
	v_mov_b32_e32 v73, v58
	v_mov_b32_e32 v58, v55
	v_lshrrev_b32_e32 v1, 1, v2
	v_lshrrev_b32_e32 v2, 2, v2
	s_add_u32 s26, s46, s25
	v_and_b32_e32 v52, 12, v2
	v_add_u32_e32 v2, s24, v0
	s_addc_u32 s27, s47, 0
	s_mov_b64 s[24:25], 0xff9c000
	v_lshl_add_u64 v[54:55], v[68:69], 0, s[24:25]
	s_add_u32 s24, s26, 0x768000
	v_and_b32_e32 v1, 32, v1
	s_addc_u32 s25, s27, 0
	s_ashr_i32 s26, s31, 1
	v_or3_b32 v52, v1, s26, v52
	v_mov_b64_e32 v[0:1], s[24:25]
	v_mad_i64_i32 v[68:69], s[24:25], v2, s33, v[0:1]
	s_add_i32 s30, s30, s77
	s_add_i32 s29, s29, s2
	s_add_i32 s28, s28, s3
	s_cmpk_gt_i32 s30, 0x15ff
	s_waitcnt vmcnt(0)
; __device__ __forceinline__ unsigned pk2(float lo, float hi) { unsigned r; asm("v_cvt_pk_bf16_f32 %0, %1, %2" : "=v"(r) : "v"(lo), "v"(hi)); return r; }
; __device__ __forceinline__ float sigmoidf_(float x) { return __builtin_amdgcn_rcpf(1.0f + __expf(-x)); }
; __device__ __forceinline__ void gemm_GU(const Params& p, int item, char* lds) {
;     ...
; #pragma unroll
;   for (int m = 0; m < 4; m++) {
;     const int rl = wr * 64 + m * 16 + fr; const float r = rsqrtf(rssg[rl] * (1.f / 1024.f) + 1e-6f);
; #pragma unroll
;     for (int i = 0; i < 2; i++) {
;       f32x4 g = acc[m][2 * i] * r, u = acc[m][2 * i + 1] * r, o;
; #pragma unroll
;       for (int j = 0; j < 4; j++) o[j] = g[j] * sigmoidf_(g[j]) * u[j];
;       const int col = (n0 >> 1) + wc * 32 + i * 16 + fq * 4;
;       u32x2 w; w[0] = pk2(o[0], o[1]); w[1] = pk2(o[2], o[3]);
;       *(u32x2*)(U + (size_t)(m0 + rl) * DFF + col) = w;
;     }
	v_fmamk_f32 v53, v74, 0x3a800000, v200
	v_mul_f32_e32 v74, 0x4b800000, v53
	v_cmp_gt_f32_e32 vcc, s83, v53
	s_nop 1
	v_cndmask_b32_e32 v53, v53, v74, vcc
	v_rsq_f32_e32 v74, v53
	v_ashrrev_i32_e32 v53, 31, v52
	v_lshlrev_b64 v[52:53], 1, v[52:53]
	v_lshl_add_u64 v[68:69], v[68:69], 0, v[52:53]
	v_mul_f32_e32 v75, 0x45800000, v74
	v_cndmask_b32_e32 v74, v74, v75, vcc
	v_pk_mul_f32 v[60:61], v[60:61], v[74:75] op_sel_hi:[1,0]
	v_pk_mul_f32 v[70:71], v[70:71], v[74:75] op_sel_hi:[1,0]
	v_pk_mul_f32 v[64:65], v[64:65], v[74:75] op_sel_hi:[1,0]
	v_pk_mul_f32 v[66:67], v[66:67], v[74:75] op_sel_hi:[1,0]
	v_mul_f32_e32 v76, 0xbfb8aa3b, v61
	v_pk_mul_f32 v[62:63], v[62:63], v[74:75] op_sel_hi:[1,0]
	v_pk_mul_f32 v[56:57], v[56:57], v[74:75] op_sel_hi:[1,0]
	v_pk_mul_f32 v[72:73], v[72:73], v[74:75] op_sel_hi:[1,0]
	v_pk_mul_f32 v[58:59], v[58:59], v[74:75] op_sel_hi:[1,0]
	v_mul_f32_e32 v74, 0xbfb8aa3b, v71
	v_mul_f32_e32 v75, 0xbfb8aa3b, v65
	v_mul_f32_e32 v77, 0xbfb8aa3b, v67
	v_exp_f32_e32 v76, v76
	v_exp_f32_e32 v74, v74
	v_exp_f32_e32 v75, v75
	v_exp_f32_e32 v77, v77
	v_add_f32_e32 v76, 1.0, v76
	v_mul_f32_e32 v79, 0xbfb8aa3b, v57
	v_add_f32_e32 v74, 1.0, v74
	v_add_f32_e32 v75, 1.0, v75
	v_add_f32_e32 v77, 1.0, v77
	v_rcp_f32_e32 v76, v76
	v_mul_f32_e32 v80, 0xbfb8aa3b, v73
	v_exp_f32_e32 v79, v79
	v_rcp_f32_e32 v74, v74
	v_rcp_f32_e32 v75, v75
	v_rcp_f32_e32 v77, v77
	v_mul_f32_e32 v78, 0xbfb8aa3b, v63
	v_mul_f32_e32 v81, 0xbfb8aa3b, v59
	v_exp_f32_e32 v80, v80
	v_exp_f32_e32 v78, v78
	v_exp_f32_e32 v81, v81
	v_mul_f32_e32 v61, v61, v76
	v_add_f32_e32 v79, 1.0, v79
	v_mul_f32_e32 v71, v71, v74
	v_mul_f32_e32 v65, v65, v75
	v_mul_f32_e32 v67, v67, v77
	v_mul_f32_e32 v61, v60, v61
	v_add_f32_e32 v80, 1.0, v80
	v_rcp_f32_e32 v79, v79
	v_mul_f32_e32 v70, v70, v71
	v_mul_f32_e32 v64, v64, v65
	v_mul_f32_e32 v65, v66, v67
	v_cvt_pk_bf16_f32 v60, v70, v64
	v_cvt_pk_bf16_f32 v61, v61, v65
	v_add_f32_e32 v78, 1.0, v78
	global_store_dwordx2 v[68:69], v[60:61], off
	v_rcp_f32_e32 v60, v80
	v_add_f32_e32 v61, 1.0, v81
	v_rcp_f32_e32 v78, v78
	v_rcp_f32_e32 v61, v61
	v_mul_f32_e32 v57, v57, v79
	v_mul_f32_e32 v56, v56, v57
	v_mul_f32_e32 v57, v73, v60
	v_mul_f32_e32 v63, v63, v78
	v_mul_f32_e32 v57, v72, v57
	v_mul_f32_e32 v59, v59, v61
	v_mul_f32_e32 v62, v62, v63
	v_mul_f32_e32 v58, v58, v59
	v_cvt_pk_bf16_f32 v56, v62, v56
	v_cvt_pk_bf16_f32 v57, v57, v58
	global_store_dwordx2 v[68:69], v[56:57], off offset:32
	global_load_dword v58, v[54:55], off offset:64
	v_mov_b32_e32 v57, v40
	v_mov_b32_e32 v40, v49
	v_mov_b32_e32 v49, v42
	v_mov_b32_e32 v42, v51
	v_mov_b32_e32 v51, v36
	v_mov_b32_e32 v36, v45
	v_mov_b32_e32 v45, v38
	v_mov_b32_e32 v38, v47
	v_mov_b32_e32 v56, v48
	v_mov_b32_e32 v48, v50
	v_mov_b32_e32 v50, v44
	v_mov_b32_e32 v44, v46
	v_add_u32_e32 v46, 16, v2
	s_waitcnt vmcnt(0)
	v_fmamk_f32 v47, v58, 0x3a800000, v200
	v_mul_f32_e32 v58, 0x4b800000, v47
	v_cmp_gt_f32_e32 vcc, s83, v47
	s_nop 1
	v_cndmask_b32_e32 v47, v47, v58, vcc
	v_rsq_f32_e32 v58, v47
	v_mad_i64_i32 v[46:47], s[24:25], v46, s33, v[0:1]
	v_lshl_add_u64 v[46:47], v[46:47], 0, v[52:53]
	v_mul_f32_e32 v59, 0x45800000, v58
	v_cndmask_b32_e32 v58, v58, v59, vcc
	v_pk_mul_f32 v[56:57], v[56:57], v[58:59] op_sel_hi:[1,0]
	v_pk_mul_f32 v[40:41], v[40:41], v[58:59] op_sel_hi:[1,0]
	v_pk_mul_f32 v[48:49], v[48:49], v[58:59] op_sel_hi:[1,0]
	v_pk_mul_f32 v[42:43], v[42:43], v[58:59] op_sel_hi:[1,0]
	v_pk_mul_f32 v[36:37], v[36:37], v[58:59] op_sel_hi:[1,0]
	v_pk_mul_f32 v[38:39], v[38:39], v[58:59] op_sel_hi:[1,0]
	v_pk_mul_f32 v[50:51], v[50:51], v[58:59] op_sel_hi:[1,0]
	v_pk_mul_f32 v[44:45], v[44:45], v[58:59] op_sel_hi:[1,0]
	v_mul_f32_e32 v58, 0xbfb8aa3b, v57
	v_mul_f32_e32 v59, 0xbfb8aa3b, v41
	v_mul_f32_e32 v60, 0xbfb8aa3b, v49
	v_mul_f32_e32 v61, 0xbfb8aa3b, v43
	v_mul_f32_e32 v63, 0xbfb8aa3b, v37
	v_mul_f32_e32 v65, 0xbfb8aa3b, v39
	v_mul_f32_e32 v62, 0xbfb8aa3b, v51
	v_mul_f32_e32 v64, 0xbfb8aa3b, v45
	v_exp_f32_e32 v58, v58
	v_exp_f32_e32 v59, v59
	v_exp_f32_e32 v60, v60
	v_exp_f32_e32 v61, v61
	v_exp_f32_e32 v63, v63
	v_exp_f32_e32 v65, v65
	v_exp_f32_e32 v62, v62
	v_exp_f32_e32 v64, v64
	v_add_f32_e32 v58, 1.0, v58
	v_add_f32_e32 v59, 1.0, v59
	v_add_f32_e32 v60, 1.0, v60
	v_add_f32_e32 v61, 1.0, v61
	v_add_f32_e32 v63, 1.0, v63
	v_add_f32_e32 v65, 1.0, v65
	v_add_f32_e32 v62, 1.0, v62
	v_add_f32_e32 v64, 1.0, v64
	v_rcp_f32_e32 v58, v58
	v_rcp_f32_e32 v59, v59
	v_rcp_f32_e32 v60, v60
	v_rcp_f32_e32 v61, v61
	v_rcp_f32_e32 v63, v63
	v_rcp_f32_e32 v65, v65
	v_rcp_f32_e32 v62, v62
	v_rcp_f32_e32 v64, v64
	v_mul_f32_e32 v57, v57, v58
	v_mul_f32_e32 v41, v41, v59
	v_mul_f32_e32 v49, v49, v60
	v_mul_f32_e32 v43, v43, v61
	v_mul_f32_e32 v37, v37, v63
	v_mul_f32_e32 v39, v39, v65
	v_mul_f32_e32 v51, v51, v62
	v_mul_f32_e32 v45, v45, v64
	v_mul_f32_e32 v56, v56, v57
	v_mul_f32_e32 v40, v40, v41
	v_mul_f32_e32 v41, v48, v49
	v_mul_f32_e32 v42, v42, v43
	v_mul_f32_e32 v48, v36, v37
	v_mul_f32_e32 v39, v38, v39
	v_cvt_pk_bf16_f32 v36, v56, v40
	v_cvt_pk_bf16_f32 v37, v41, v42
	v_mul_f32_e32 v43, v50, v51
	v_mul_f32_e32 v44, v44, v45
	v_cvt_pk_bf16_f32 v38, v43, v48
	v_cvt_pk_bf16_f32 v39, v44, v39
	global_store_dwordx2 v[46:47], v[36:37], off
	global_store_dwordx2 v[46:47], v[38:39], off offset:32
	global_load_dword v38, v[54:55], off offset:128
	v_mov_b32_e32 v37, v24
	v_mov_b32_e32 v24, v33
	v_mov_b32_e32 v33, v26
	v_mov_b32_e32 v26, v35
	v_mov_b32_e32 v35, v20
	v_mov_b32_e32 v20, v29
	v_mov_b32_e32 v29, v22
	v_mov_b32_e32 v22, v31
	v_mov_b32_e32 v36, v32
	v_mov_b32_e32 v32, v34
	v_mov_b32_e32 v34, v28
	v_mov_b32_e32 v28, v30
	v_add_u32_e32 v30, 32, v2
	v_add_u32_e32 v2, 48, v2
	s_waitcnt vmcnt(0)
; __device__ __forceinline__ unsigned pk2(float lo, float hi) { unsigned r; asm("v_cvt_pk_bf16_f32 %0, %1, %2" : "=v"(r) : "v"(lo), "v"(hi)); return r; }
; __device__ __forceinline__ float sigmoidf_(float x) { return __builtin_amdgcn_rcpf(1.0f + __expf(-x)); }
; __device__ __forceinline__ void gemm_GU(const Params& p, int item, char* lds) {
;     ...
; #pragma unroll
;   for (int m = 0; m < 4; m++) {
;     const int rl = wr * 64 + m * 16 + fr; const float r = rsqrtf(rssg[rl] * (1.f / 1024.f) + 1e-6f);
; #pragma unroll
;     for (int i = 0; i < 2; i++) {
;       f32x4 g = acc[m][2 * i] * r, u = acc[m][2 * i + 1] * r, o;
; #pragma unroll
;       for (int j = 0; j < 4; j++) o[j] = g[j] * sigmoidf_(g[j]) * u[j];
;       const int col = (n0 >> 1) + wc * 32 + i * 16 + fq * 4;
;       u32x2 w; w[0] = pk2(o[0], o[1]); w[1] = pk2(o[2], o[3]);
;       *(u32x2*)(U + (size_t)(m0 + rl) * DFF + col) = w;
;     }
;   }
;   __syncthreads();
	v_fmamk_f32 v31, v38, 0x3a800000, v200
	v_mul_f32_e32 v38, 0x4b800000, v31
	v_cmp_gt_f32_e32 vcc, s83, v31
	s_nop 1
	v_cndmask_b32_e32 v31, v31, v38, vcc
	v_rsq_f32_e32 v38, v31
	v_mad_i64_i32 v[30:31], s[24:25], v30, s33, v[0:1]
	v_lshl_add_u64 v[30:31], v[30:31], 0, v[52:53]
	v_mul_f32_e32 v39, 0x45800000, v38
	v_cndmask_b32_e32 v38, v38, v39, vcc
	v_pk_mul_f32 v[36:37], v[36:37], v[38:39] op_sel_hi:[1,0]
	v_pk_mul_f32 v[24:25], v[24:25], v[38:39] op_sel_hi:[1,0]
	v_pk_mul_f32 v[32:33], v[32:33], v[38:39] op_sel_hi:[1,0]
	v_pk_mul_f32 v[26:27], v[26:27], v[38:39] op_sel_hi:[1,0]
	v_pk_mul_f32 v[20:21], v[20:21], v[38:39] op_sel_hi:[1,0]
	v_pk_mul_f32 v[22:23], v[22:23], v[38:39] op_sel_hi:[1,0]
	v_pk_mul_f32 v[34:35], v[34:35], v[38:39] op_sel_hi:[1,0]
	v_pk_mul_f32 v[28:29], v[28:29], v[38:39] op_sel_hi:[1,0]
	v_mul_f32_e32 v38, 0xbfb8aa3b, v37
	v_mul_f32_e32 v39, 0xbfb8aa3b, v25
	v_mul_f32_e32 v40, 0xbfb8aa3b, v33
	v_mul_f32_e32 v41, 0xbfb8aa3b, v27
	v_mul_f32_e32 v43, 0xbfb8aa3b, v21
	v_mul_f32_e32 v45, 0xbfb8aa3b, v23
	v_mul_f32_e32 v42, 0xbfb8aa3b, v35
	v_mul_f32_e32 v44, 0xbfb8aa3b, v29
	v_exp_f32_e32 v38, v38
	v_exp_f32_e32 v39, v39
	v_exp_f32_e32 v40, v40
	v_exp_f32_e32 v41, v41
	v_exp_f32_e32 v43, v43
	v_exp_f32_e32 v45, v45
	v_exp_f32_e32 v42, v42
	v_exp_f32_e32 v44, v44
	v_add_f32_e32 v38, 1.0, v38
	v_add_f32_e32 v39, 1.0, v39
	v_add_f32_e32 v40, 1.0, v40
	v_add_f32_e32 v41, 1.0, v41
	v_add_f32_e32 v43, 1.0, v43
	v_add_f32_e32 v45, 1.0, v45
	v_add_f32_e32 v42, 1.0, v42
	v_add_f32_e32 v44, 1.0, v44
	v_rcp_f32_e32 v38, v38
	v_rcp_f32_e32 v39, v39
	v_rcp_f32_e32 v40, v40
	v_rcp_f32_e32 v41, v41
	v_rcp_f32_e32 v43, v43
	v_rcp_f32_e32 v45, v45
	v_rcp_f32_e32 v42, v42
	v_rcp_f32_e32 v44, v44
	v_mul_f32_e32 v37, v37, v38
	v_mul_f32_e32 v25, v25, v39
	v_mul_f32_e32 v33, v33, v40
	v_mul_f32_e32 v27, v27, v41
	v_mul_f32_e32 v21, v21, v43
	v_mul_f32_e32 v23, v23, v45
	v_mul_f32_e32 v35, v35, v42
	v_mul_f32_e32 v29, v29, v44
	v_mul_f32_e32 v36, v36, v37
	v_mul_f32_e32 v24, v24, v25
	v_mul_f32_e32 v25, v32, v33
	v_mul_f32_e32 v26, v26, v27
	v_mul_f32_e32 v32, v20, v21
	v_mul_f32_e32 v23, v22, v23
	v_cvt_pk_bf16_f32 v20, v36, v24
	v_cvt_pk_bf16_f32 v21, v25, v26
	v_mul_f32_e32 v27, v34, v35
	v_mul_f32_e32 v28, v28, v29
	v_cvt_pk_bf16_f32 v22, v27, v32
	v_cvt_pk_bf16_f32 v23, v28, v23
	global_store_dwordx2 v[30:31], v[20:21], off
	global_store_dwordx2 v[30:31], v[22:23], off offset:32
	global_load_dword v22, v[54:55], off offset:192
	v_mov_b32_e32 v20, v16
	v_mov_b32_e32 v16, v18
	v_mov_b32_e32 v18, v12
	v_mov_b32_e32 v12, v14
	v_mov_b32_e32 v21, v8
	v_mov_b32_e32 v8, v17
	v_mov_b32_e32 v17, v10
	v_mov_b32_e32 v10, v19
	v_mov_b32_e32 v19, v4
	v_mov_b32_e32 v4, v13
	v_mov_b32_e32 v13, v6
	v_mov_b32_e32 v6, v15
	v_mad_i64_i32 v[0:1], s[24:25], v2, s33, v[0:1]
	v_lshl_add_u64 v[0:1], v[0:1], 0, v[52:53]
	s_waitcnt vmcnt(0)
	v_fmamk_f32 v14, v22, 0x3a800000, v200
	v_mul_f32_e32 v15, 0x4b800000, v14
	v_cmp_gt_f32_e32 vcc, s83, v14
	s_nop 1
	v_cndmask_b32_e32 v14, v14, v15, vcc
	v_rsq_f32_e32 v14, v14
	s_nop 0
	v_mul_f32_e32 v2, 0x45800000, v14
	v_cndmask_b32_e32 v2, v14, v2, vcc
	v_pk_mul_f32 v[14:15], v[20:21], v[2:3] op_sel_hi:[1,0]
	v_pk_mul_f32 v[8:9], v[8:9], v[2:3] op_sel_hi:[1,0]
	v_pk_mul_f32 v[16:17], v[16:17], v[2:3] op_sel_hi:[1,0]
	v_pk_mul_f32 v[10:11], v[10:11], v[2:3] op_sel_hi:[1,0]
	v_pk_mul_f32 v[4:5], v[4:5], v[2:3] op_sel_hi:[1,0]
	v_pk_mul_f32 v[6:7], v[6:7], v[2:3] op_sel_hi:[1,0]
	v_pk_mul_f32 v[18:19], v[18:19], v[2:3] op_sel_hi:[1,0]
	v_pk_mul_f32 v[12:13], v[12:13], v[2:3] op_sel_hi:[1,0]
	v_mul_f32_e32 v2, 0xbfb8aa3b, v15
	v_mul_f32_e32 v20, 0xbfb8aa3b, v9
	v_mul_f32_e32 v21, 0xbfb8aa3b, v17
	v_mul_f32_e32 v22, 0xbfb8aa3b, v11
	v_mul_f32_e32 v24, 0xbfb8aa3b, v5
	v_mul_f32_e32 v26, 0xbfb8aa3b, v7
	v_mul_f32_e32 v23, 0xbfb8aa3b, v19
	v_mul_f32_e32 v25, 0xbfb8aa3b, v13
	v_exp_f32_e32 v2, v2
	v_exp_f32_e32 v20, v20
	v_exp_f32_e32 v21, v21
	v_exp_f32_e32 v22, v22
	v_exp_f32_e32 v24, v24
	v_exp_f32_e32 v26, v26
	v_exp_f32_e32 v23, v23
	v_exp_f32_e32 v25, v25
	v_add_f32_e32 v2, 1.0, v2
	v_add_f32_e32 v20, 1.0, v20
	v_add_f32_e32 v21, 1.0, v21
	v_add_f32_e32 v22, 1.0, v22
	v_add_f32_e32 v24, 1.0, v24
	v_add_f32_e32 v26, 1.0, v26
	v_add_f32_e32 v23, 1.0, v23
	v_add_f32_e32 v25, 1.0, v25
	v_rcp_f32_e32 v2, v2
	v_rcp_f32_e32 v20, v20
	v_rcp_f32_e32 v21, v21
	v_rcp_f32_e32 v22, v22
	v_rcp_f32_e32 v24, v24
	v_rcp_f32_e32 v26, v26
	v_rcp_f32_e32 v23, v23
	v_rcp_f32_e32 v25, v25
	v_mul_f32_e32 v2, v15, v2
	v_mul_f32_e32 v9, v9, v20
	v_mul_f32_e32 v15, v17, v21
	v_mul_f32_e32 v11, v11, v22
	v_mul_f32_e32 v5, v5, v24
	v_mul_f32_e32 v7, v7, v26
	v_mul_f32_e32 v17, v19, v23
	v_mul_f32_e32 v13, v13, v25
	v_mul_f32_e32 v2, v14, v2
	v_mul_f32_e32 v8, v8, v9
	v_mul_f32_e32 v9, v16, v15
	v_mul_f32_e32 v10, v10, v11
	v_mul_f32_e32 v14, v4, v5
	v_mul_f32_e32 v7, v6, v7
	v_cvt_pk_bf16_f32 v4, v2, v8
	v_cvt_pk_bf16_f32 v5, v9, v10
	v_mul_f32_e32 v11, v18, v17
	v_mul_f32_e32 v12, v12, v13
	v_cvt_pk_bf16_f32 v6, v11, v14
	v_cvt_pk_bf16_f32 v7, v12, v7
	global_store_dwordx2 v[0:1], v[4:5], off
	global_store_dwordx2 v[0:1], v[6:7], off offset:32
	s_barrier
	s_cbranch_scc0 .LBB0_108

; __device__ __forceinline__ void gemm_mainloop_d(const bf16_t* __restrict__ Ap, int lda, const bf16_t* __restrict__ Bt, int K,
;                                                 int m0, int n0, f32x4 (&acc)[4][4], char* lds) {
;     ...
;   for (int kt = 0; kt < nk; kt++) {
;     const int st = kt & 1;
;     if (kt + 1 < nk) dma(kt + 1, st ^ 1);
;     const char* la = lds + st * 32768; const char* lb = la + 16384;
;     bf16x8 af[2][4], bfv[2][4];
; #pragma unroll
;     for (int kc = 0; kc < 2; kc++) {
; #pragma unroll
;       for (int m = 0; m < 4; m++) { const int row = wr * 64 + m * 16 + fr; af[kc][m] = *(const bf16x8*)(la + (row * 8 + ((kc * 4 + fq) ^ ((row >> 1) & 7))) * 16); }
; #pragma unroll
;       for (int n = 0; n < 4; n++) { const int row = wc * 64 + n * 16 + fr; bfv[kc][n] = *(const bf16x8*)(lb + (row * 8 + ((kc * 4 + fq) ^ ((row >> 1) & 7))) * 16); }
;     }
;     __builtin_amdgcn_s_setprio(1);
; #pragma unroll
;     for (int kc = 0; kc < 2; kc++)
; #pragma unroll
;       for (int m = 0; m < 4; m++)
; #pragma unroll
;         for (int n = 0; n < 4; n++) acc[m][n] = __builtin_amdgcn_mfma_f32_16x16x32_bf16(bfv[kc][n], af[kc][m], acc[m][n], 0, 0, 0);
;     __builtin_amdgcn_s_setprio(0);
;     asm volatile("s_waitcnt vmcnt(0) lgkmcnt(0)" ::: "memory"); __builtin_amdgcn_s_barrier(); asm volatile("" ::: "memory");
.LBB0_126:
	s_and_b32 s37, s34, 0x8000
	s_xor_b32 s43, s37, 0x8000
	s_add_i32 s43, s43, vcc_hi
	s_mov_b32 m0, s43
	s_add_i32 vcc_lo, s43, 0x4000
	global_load_lds_dwordx4 v150, s[46:47]
	s_mov_b32 m0, vcc_lo
	s_add_i32 vcc_lo, s43, 0x1000
	global_load_lds_dwordx4 v151, s[46:47]
	s_mov_b32 m0, vcc_lo
	s_add_i32 vcc_lo, s43, 0x5000
	global_load_lds_dwordx4 v152, s[46:47]
	s_mov_b32 m0, vcc_lo
	s_add_i32 vcc_lo, s43, 0x2000
	global_load_lds_dwordx4 v153, s[46:47]
	s_mov_b32 m0, vcc_lo
	s_add_i32 vcc_lo, s43, 0x6000
	global_load_lds_dwordx4 v154, s[46:47]
	s_mov_b32 m0, vcc_lo
	s_add_i32 vcc_lo, s43, 0x3000
	global_load_lds_dwordx4 v155, s[46:47]
	s_mov_b32 m0, vcc_lo
	s_add_i32 vcc_lo, s43, 0x7000
	global_load_lds_dwordx4 v156, s[46:47]
	s_mov_b32 m0, vcc_lo
	s_nop 0
	global_load_lds_dwordx4 v157, s[46:47]
	v_add_u32_e32 v150, 0x80, v150
	v_add_u32_e32 v151, 0x80, v151
	v_add_u32_e32 v152, 0x80, v152
	v_add_u32_e32 v153, 0x80, v153
	v_add_u32_e32 v154, 0x80, v154
	v_add_u32_e32 v155, 0x80, v155
	v_add_u32_e32 v156, 0x80, v156
	v_add_u32_e32 v157, 0x80, v157
	v_add_u32_e32 v98, s37, v85
	v_add_u32_e32 v114, s37, v84
	v_add_u32_e32 v130, s37, v83
	v_add_u32_e32 v146, s37, v2
	ds_read_b128 v[86:89], v98
	ds_read_b128 v[90:93], v98 offset:2048
	ds_read_b128 v[94:97], v98 offset:4096
	ds_read_b128 v[98:101], v98 offset:6144
	ds_read_b128 v[102:105], v114 offset:16384
	ds_read_b128 v[106:109], v114 offset:18432
	ds_read_b128 v[110:113], v114 offset:20480
	ds_read_b128 v[114:117], v114 offset:22528
	ds_read_b128 v[118:121], v130
	ds_read_b128 v[122:125], v130 offset:2048
	ds_read_b128 v[126:129], v130 offset:4096
	ds_read_b128 v[130:133], v130 offset:6144
	ds_read_b128 v[134:137], v146 offset:16384
	ds_read_b128 v[138:141], v146 offset:18432
	ds_read_b128 v[142:145], v146 offset:20480
	ds_read_b128 v[146:149], v146 offset:22528
	s_waitcnt lgkmcnt(0)
	v_mfma_f32_16x16x32_bf16 v[64:67], v[102:105], v[86:89], v[64:67]
	v_mfma_f32_16x16x32_bf16 v[60:63], v[106:109], v[86:89], v[60:63]
	v_mfma_f32_16x16x32_bf16 v[56:59], v[110:113], v[86:89], v[56:59]
	v_mfma_f32_16x16x32_bf16 v[52:55], v[114:117], v[86:89], v[52:55]
	v_mfma_f32_16x16x32_bf16 v[48:51], v[102:105], v[90:93], v[48:51]
	v_mfma_f32_16x16x32_bf16 v[44:47], v[106:109], v[90:93], v[44:47]
	v_mfma_f32_16x16x32_bf16 v[40:43], v[110:113], v[90:93], v[40:43]
	v_mfma_f32_16x16x32_bf16 v[36:39], v[114:117], v[90:93], v[36:39]
	v_mfma_f32_16x16x32_bf16 v[32:35], v[102:105], v[94:97], v[32:35]
	v_mfma_f32_16x16x32_bf16 v[28:31], v[106:109], v[94:97], v[28:31]
	v_mfma_f32_16x16x32_bf16 v[24:27], v[110:113], v[94:97], v[24:27]
	v_mfma_f32_16x16x32_bf16 v[20:23], v[114:117], v[94:97], v[20:23]
	v_mfma_f32_16x16x32_bf16 v[16:19], v[102:105], v[98:101], v[16:19]
	v_mfma_f32_16x16x32_bf16 v[12:15], v[106:109], v[98:101], v[12:15]
	v_mfma_f32_16x16x32_bf16 v[8:11], v[110:113], v[98:101], v[8:11]
	v_mfma_f32_16x16x32_bf16 v[4:7], v[114:117], v[98:101], v[4:7]
	v_mfma_f32_16x16x32_bf16 v[64:67], v[134:137], v[118:121], v[64:67]
	v_mfma_f32_16x16x32_bf16 v[60:63], v[138:141], v[118:121], v[60:63]
	v_mfma_f32_16x16x32_bf16 v[56:59], v[142:145], v[118:121], v[56:59]
	v_mfma_f32_16x16x32_bf16 v[52:55], v[146:149], v[118:121], v[52:55]
	v_mfma_f32_16x16x32_bf16 v[48:51], v[134:137], v[122:125], v[48:51]
	v_mfma_f32_16x16x32_bf16 v[44:47], v[138:141], v[122:125], v[44:47]
	v_mfma_f32_16x16x32_bf16 v[40:43], v[142:145], v[122:125], v[40:43]
	v_mfma_f32_16x16x32_bf16 v[36:39], v[146:149], v[122:125], v[36:39]
	v_mfma_f32_16x16x32_bf16 v[32:35], v[134:137], v[126:129], v[32:35]
	v_mfma_f32_16x16x32_bf16 v[28:31], v[138:141], v[126:129], v[28:31]
	v_mfma_f32_16x16x32_bf16 v[24:27], v[142:145], v[126:129], v[24:27]
	v_mfma_f32_16x16x32_bf16 v[20:23], v[146:149], v[126:129], v[20:23]
	v_mfma_f32_16x16x32_bf16 v[16:19], v[134:137], v[130:133], v[16:19]
	v_mfma_f32_16x16x32_bf16 v[12:15], v[138:141], v[130:133], v[12:15]
	v_mfma_f32_16x16x32_bf16 v[8:11], v[142:145], v[130:133], v[8:11]
	v_mfma_f32_16x16x32_bf16 v[4:7], v[146:149], v[130:133], v[4:7]
	s_waitcnt vmcnt(0) lgkmcnt(0)
	s_barrier
	s_add_u32 s30, s30, 0x80
	s_addc_u32 s31, s31, 0
	s_add_i32 s34, s34, 0x8000
	s_cmpk_eq_i32 s30, 0x780
	s_cbranch_scc0 .LBB0_126
	v_add_u32_e32 v0, 0, v85
	ds_read_b128 v[68:71], v0 offset:32768
	ds_read_b128 v[72:75], v0 offset:34816
	ds_read_b128 v[76:79], v0 offset:36864
	ds_read_b128 v[86:89], v0 offset:38912
	v_add_u32_e32 v0, 0, v84
	ds_read_b128 v[90:93], v0 offset:49152
	ds_read_b128 v[94:97], v0 offset:51200
	ds_read_b128 v[98:101], v0 offset:53248
	ds_read_b128 v[102:105], v0 offset:55296
	v_add_u32_e32 v0, 0, v83
	s_add_u32 s30, s46, s35
	ds_read_b128 v[80:83], v0 offset:32768
	ds_read_b128 v[106:109], v0 offset:34816
	ds_read_b128 v[110:113], v0 offset:36864
	ds_read_b128 v[114:117], v0 offset:38912
	v_add_u32_e32 v0, 0, v2
	s_addc_u32 s31, s47, 0
	ds_read_b128 v[118:121], v0 offset:49152
	ds_read_b128 v[122:125], v0 offset:51200
	ds_read_b128 v[126:129], v0 offset:53248
	ds_read_b128 v[130:133], v0 offset:55296
	s_add_u32 s36, s46, s36
	s_addc_u32 s37, s47, 0
	s_add_u32 s34, s30, 0x65a8000
	s_addc_u32 s35, s31, 0
	s_add_u32 s30, s36, 0xff9c000
	s_addc_u32 s31, s37, 0
	s_waitcnt lgkmcnt(0)
; __device__ __forceinline__ unsigned pk2(float lo, float hi) { unsigned r; asm("v_cvt_pk_bf16_f32 %0, %1, %2" : "=v"(r) : "v"(lo), "v"(hi)); return r; }
; __device__ __forceinline__ float bflo(unsigned u) { return __uint_as_float(u << 16); }
; __device__ __forceinline__ float bfhi(unsigned u) { return __uint_as_float(u & 0xffff0000u); }
; __device__ __forceinline__ void gemm_mainloop_d(const bf16_t* __restrict__ Ap, int lda, const bf16_t* __restrict__ Bt, int K,
;                                                 int m0, int n0, f32x4 (&acc)[4][4], char* lds) {
;     ...
;     for (int kc = 0; kc < 2; kc++)
; #pragma unroll
;       for (int m = 0; m < 4; m++)
; #pragma unroll
;         for (int n = 0; n < 4; n++) acc[m][n] = __builtin_amdgcn_mfma_f32_16x16x32_bf16(bfv[kc][n], af[kc][m], acc[m][n], 0, 0, 0);
;     __builtin_amdgcn_s_setprio(0);
;     asm volatile("s_waitcnt vmcnt(0) lgkmcnt(0)" ::: "memory"); __builtin_amdgcn_s_barrier(); asm volatile("" ::: "memory");
; __device__ __forceinline__ void gemm_RES(const bf16_t* A, int K, const bf16_t* Bt, const float* xin, float* xout, bf16_t* xb, float* rss, int item, char* lds) {
;     ...
; #pragma unroll
;   for (int m = 0; m < 4; m++) {
;     const int rowg = m0 + wr * 64 + m * 16 + fr;
;     const size_t ro = (size_t)rowg * DM;
;     float sq = 0.f;
; #pragma unroll
;     for (int n = 0; n < 4; n++) {
;       const int col = n0 + wc * 64 + n * 16 + fq * 4;
;       f32x4 xv = *(const f32x4*)(xin + ro + col);
;       const f32x4 xn = xv + acc[m][n];
;       *(f32x4*)(xout + ro + col) = xn;
;       u32x2 w; w[0] = pk2(xn[0], xn[1]); w[1] = pk2(xn[2], xn[3]); *(u32x2*)(xb + ro + col) = w;
;       const float b0 = bflo(w[0]), b1 = bfhi(w[0]), b2 = bflo(w[1]), b3 = bfhi(w[1]);
;       sq += b0 * b0 + b1 * b1 + b2 * b2 + b3 * b3;
;     }
;     sq += __shfl_xor(sq, 16); sq += __shfl_xor(sq, 32);
;     if (fq == 0) unsafeAtomicAdd(rss + rowg, sq);
;   }
	v_mfma_f32_16x16x32_bf16 v[56:59], v[98:101], v[68:71], v[56:59]
	v_mfma_f32_16x16x32_bf16 v[48:51], v[90:93], v[72:75], v[48:51]
	v_mfma_f32_16x16x32_bf16 v[44:47], v[94:97], v[72:75], v[44:47]
	v_mfma_f32_16x16x32_bf16 v[40:43], v[98:101], v[72:75], v[40:43]
	v_mfma_f32_16x16x32_bf16 v[36:39], v[102:105], v[72:75], v[36:39]
	v_mfma_f32_16x16x32_bf16 v[32:35], v[90:93], v[76:79], v[32:35]
	v_mfma_f32_16x16x32_bf16 v[28:31], v[94:97], v[76:79], v[28:31]
	v_mfma_f32_16x16x32_bf16 v[24:27], v[98:101], v[76:79], v[24:27]
	v_mfma_f32_16x16x32_bf16 v[20:23], v[102:105], v[76:79], v[20:23]
	v_mfma_f32_16x16x32_bf16 v[16:19], v[90:93], v[86:89], v[16:19]
	v_mfma_f32_16x16x32_bf16 v[12:15], v[94:97], v[86:89], v[12:15]
	v_mfma_f32_16x16x32_bf16 v[8:11], v[98:101], v[86:89], v[8:11]
	v_mfma_f32_16x16x32_bf16 v[4:7], v[102:105], v[86:89], v[4:7]
	v_mfma_f32_16x16x32_bf16 v[64:67], v[90:93], v[68:71], v[64:67]
	v_mfma_f32_16x16x32_bf16 v[60:63], v[94:97], v[68:71], v[60:63]
	v_mfma_f32_16x16x32_bf16 v[52:55], v[102:105], v[68:71], v[52:55]
	v_mfma_f32_16x16x32_bf16 v[56:59], v[126:129], v[80:83], v[56:59]
	v_mfma_f32_16x16x32_bf16 v[48:51], v[118:121], v[106:109], v[48:51]
	v_mfma_f32_16x16x32_bf16 v[44:47], v[122:125], v[106:109], v[44:47]
	v_mfma_f32_16x16x32_bf16 v[40:43], v[126:129], v[106:109], v[40:43]
	v_mfma_f32_16x16x32_bf16 v[36:39], v[130:133], v[106:109], v[36:39]
	v_mfma_f32_16x16x32_bf16 v[32:35], v[118:121], v[110:113], v[32:35]
	v_mfma_f32_16x16x32_bf16 v[28:31], v[122:125], v[110:113], v[28:31]
	v_mfma_f32_16x16x32_bf16 v[24:27], v[126:129], v[110:113], v[24:27]
	v_mfma_f32_16x16x32_bf16 v[20:23], v[130:133], v[110:113], v[20:23]
	v_mfma_f32_16x16x32_bf16 v[16:19], v[118:121], v[114:117], v[16:19]
	v_mfma_f32_16x16x32_bf16 v[12:15], v[122:125], v[114:117], v[12:15]
	v_mfma_f32_16x16x32_bf16 v[8:11], v[126:129], v[114:117], v[8:11]
	v_mfma_f32_16x16x32_bf16 v[4:7], v[130:133], v[114:117], v[4:7]
	v_mfma_f32_16x16x32_bf16 v[64:67], v[118:121], v[80:83], v[64:67]
	v_mfma_f32_16x16x32_bf16 v[60:63], v[122:125], v[80:83], v[60:63]
	v_mfma_f32_16x16x32_bf16 v[68:71], v[130:133], v[80:83], v[52:55]
	v_mov_b32_e32 v0, v198
	s_waitcnt vmcnt(0) lgkmcnt(0)
	s_barrier
	v_readlane_b32 s4, v252, 35
	v_ashrrev_i32_e32 v2, 1, v0
	v_and_b32_e32 v2, 0xffffffc0, v2
	v_add_u32_e32 v2, s3, v2
	v_bfe_u32 v82, v0, 4, 2
	v_and_or_b32 v52, v0, 15, v2
	v_and_b32_e32 v1, 64, v0
	v_lshlrev_b32_e32 v0, 2, v82
	v_ashrrev_i32_e32 v53, 31, v52
	v_or3_b32 v78, v0, v1, s2
	v_lshlrev_b64 v[54:55], 12, v[52:53]
	v_lshl_add_u64 v[0:1], s[26:27], 0, v[54:55]
	v_lshlrev_b32_e32 v2, 2, v78
	v_lshl_add_u64 v[76:77], v[0:1], 0, v[2:3]
	global_load_dwordx4 v[72:75], v[76:77], off
	v_lshlrev_b32_e32 v0, 1, v78
	v_lshlrev_b64 v[78:79], 11, v[52:53]
	v_readlane_b32 s18, v252, 49
	v_readlane_b32 s19, v252, 50
	v_mov_b32_e32 v1, v3
	v_lshl_add_u64 v[78:79], s[34:35], 0, v[78:79]
	v_lshl_add_u64 v[54:55], s[18:19], 0, v[54:55]
	v_lshl_add_u64 v[80:81], v[54:55], 0, v[2:3]
	v_lshl_add_u64 v[78:79], v[78:79], 0, v[0:1]
	v_readlane_b32 s5, v252, 36
	v_readlane_b32 s6, v252, 37
	v_readlane_b32 s7, v252, 38
	v_readlane_b32 s8, v252, 39
	v_readlane_b32 s9, v252, 40
	v_readlane_b32 s10, v252, 41
	v_readlane_b32 s11, v252, 42
	v_readlane_b32 s12, v252, 43
	v_readlane_b32 s13, v252, 44
	v_readlane_b32 s14, v252, 45
	v_readlane_b32 s15, v252, 46
	v_readlane_b32 s16, v252, 47
	v_readlane_b32 s17, v252, 48
	s_waitcnt vmcnt(0)
	v_pk_add_f32 v[66:67], v[66:67], v[74:75]
	v_pk_add_f32 v[64:65], v[64:65], v[72:73]
	global_store_dwordx4 v[80:81], v[64:67], off
	v_cvt_pk_bf16_f32 v54, v64, v65
	v_cvt_pk_bf16_f32 v55, v66, v67
	global_store_dwordx2 v[78:79], v[54:55], off
	global_load_dwordx4 v[64:67], v[76:77], off offset:64
	s_waitcnt vmcnt(0)
	v_pk_add_f32 v[62:63], v[62:63], v[66:67]
	v_pk_add_f32 v[60:61], v[60:61], v[64:65]
	global_store_dwordx4 v[80:81], v[60:63], off offset:64
	v_cvt_pk_bf16_f32 v64, v60, v61
	v_cvt_pk_bf16_f32 v65, v62, v63
	global_store_dwordx2 v[78:79], v[64:65], off offset:32
	global_load_dwordx4 v[60:63], v[76:77], off offset:128
	v_lshlrev_b32_e32 v66, 16, v54
	v_and_b32_e32 v54, 0xffff0000, v54
	v_mul_f32_e32 v54, v54, v54
	v_lshlrev_b32_e32 v67, 16, v55
	v_fmac_f32_e32 v54, v66, v66
	v_and_b32_e32 v55, 0xffff0000, v55
	v_fmac_f32_e32 v54, v67, v67
	v_fmac_f32_e32 v54, v55, v55
	v_lshlrev_b32_e32 v55, 16, v64
	v_and_b32_e32 v64, 0xffff0000, v64
	v_mul_f32_e32 v64, v64, v64
	v_lshlrev_b32_e32 v66, 16, v65
	v_fmac_f32_e32 v64, v55, v55
	v_and_b32_e32 v65, 0xffff0000, v65
	v_fmac_f32_e32 v64, v66, v66
	v_fmac_f32_e32 v64, v65, v65
	v_add_f32_e32 v54, v54, v64
	s_waitcnt vmcnt(0)
	v_pk_add_f32 v[58:59], v[58:59], v[62:63]
	v_pk_add_f32 v[56:57], v[56:57], v[60:61]
	global_store_dwordx4 v[80:81], v[56:59], off offset:128
	v_cvt_pk_bf16_f32 v62, v56, v57
	v_cvt_pk_bf16_f32 v63, v58, v59
	global_store_dwordx2 v[78:79], v[62:63], off offset:64
	global_load_dwordx4 v[58:61], v[76:77], off offset:192
	v_lshlrev_b32_e32 v55, 16, v62
	v_and_b32_e32 v62, 0xffff0000, v62
	v_mul_f32_e32 v62, v62, v62
	v_lshlrev_b32_e32 v64, 16, v63
	v_fmac_f32_e32 v62, v55, v55
	v_and_b32_e32 v63, 0xffff0000, v63
	v_fmac_f32_e32 v62, v64, v64
	v_fmac_f32_e32 v62, v63, v63
	v_add_f32_e32 v54, v54, v62
	v_and_b32_e32 v57, 64, v218
	v_xor_b32_e32 v56, 16, v218
	v_add_u32_e32 v57, 64, v57
	v_cmp_lt_i32_e32 vcc, v56, v57
	s_waitcnt vmcnt(0)
	v_pk_add_f32 v[58:59], v[68:69], v[58:59]
	s_nop 0
	v_cvt_pk_bf16_f32 v62, v58, v59
	v_pk_add_f32 v[60:61], v[70:71], v[60:61]
	v_and_b32_e32 v64, 0xffff0000, v62
	v_lshlrev_b32_e32 v55, 16, v62
	v_mul_f32_e32 v64, v64, v64
	v_cvt_pk_bf16_f32 v63, v60, v61
	v_fmac_f32_e32 v64, v55, v55
	v_lshlrev_b32_e32 v65, 16, v63
	v_and_b32_e32 v66, 0xffff0000, v63
	v_fmac_f32_e32 v64, v65, v65
	v_cndmask_b32_e32 v56, v218, v56, vcc
	v_fmac_f32_e32 v64, v66, v66
	v_lshlrev_b32_e32 v56, 2, v56
	v_add_f32_e32 v54, v54, v64
	ds_bpermute_b32 v55, v56, v54
	v_xor_b32_e32 v64, 32, v218
	v_cmp_lt_i32_e32 vcc, v64, v57
	global_store_dwordx4 v[80:81], v[58:61], off offset:192
	global_store_dwordx2 v[78:79], v[62:63], off offset:96
	v_cndmask_b32_e32 v57, v218, v64, vcc
	s_waitcnt lgkmcnt(0)
	v_add_f32_e32 v54, v54, v55
	v_lshlrev_b32_e32 v57, 2, v57
	ds_bpermute_b32 v55, v57, v54
	v_cmp_eq_u32_e32 vcc, 0, v82
	s_and_saveexec_b64 s[36:37], vcc
	s_cbranch_execz .LBB0_129
	v_lshl_add_u64 v[58:59], v[52:53], 2, s[30:31]
	s_waitcnt lgkmcnt(0)
	v_add_f32_e32 v53, v54, v55
	global_atomic_add_f32 v[58:59], v53, off

; __device__ __forceinline__ void run_phase(const Params& p, int ph, char* lds, int mode) {
;     ...
;       for (int it = B; it < 128 * 18; it += G) if (EN(1)) gemm_A(p, it, lds);
.LBB0_652:
	s_or_b64 exec, exec, s[24:25]
	v_readlane_b32 s2, v254, 33
	v_readlane_b32 s3, v254, 34
	s_andn2_b64 vcc, exec, s[2:3]
	s_cbranch_vccnz .LBB0_705
	v_readlane_b32 s66, v252, 0
	v_readlane_b32 vcc_lo, v252, 0
	s_nop 0
	s_cmpk_lt_u32 vcc_lo, 0x100
	s_cbranch_scc0 .Lmy_sp_a
	s_setprio 1
.Lmy_sp_a:
	s_branch .LBB0_656
.LBB0_654:
	s_or_b64 exec, exec, s[24:25]

; __device__ __forceinline__ void gemm_mainloop_d(const bf16_t* __restrict__ Ap, int lda, const bf16_t* __restrict__ Bt, int K,
;                                                 int m0, int n0, f32x4 (&acc)[4][4], char* lds) {
;     ...
;   for (int kt = 0; kt < nk; kt++) {
;     const int st = kt & 1;
;     if (kt + 1 < nk) dma(kt + 1, st ^ 1);
;     const char* la = lds + st * 32768; const char* lb = la + 16384;
;     bf16x8 af[2][4], bfv[2][4];
; #pragma unroll
;     for (int kc = 0; kc < 2; kc++) {
; #pragma unroll
;       for (int m = 0; m < 4; m++) { const int row = wr * 64 + m * 16 + fr; af[kc][m] = *(const bf16x8*)(la + (row * 8 + ((kc * 4 + fq) ^ ((row >> 1) & 7))) * 16); }
; #pragma unroll
;       for (int n = 0; n < 4; n++) { const int row = wc * 64 + n * 16 + fr; bfv[kc][n] = *(const bf16x8*)(lb + (row * 8 + ((kc * 4 + fq) ^ ((row >> 1) & 7))) * 16); }
;     }
;     __builtin_amdgcn_s_setprio(1);
; #pragma unroll
;     for (int kc = 0; kc < 2; kc++)
; #pragma unroll
;       for (int m = 0; m < 4; m++)
; #pragma unroll
;         for (int n = 0; n < 4; n++) acc[m][n] = __builtin_amdgcn_mfma_f32_16x16x32_bf16(bfv[kc][n], af[kc][m], acc[m][n], 0, 0, 0);
;     __builtin_amdgcn_s_setprio(0);
;     asm volatile("s_waitcnt vmcnt(0) lgkmcnt(0)" ::: "memory"); __builtin_amdgcn_s_barrier(); asm volatile("" ::: "memory");
.LBB0_657:
	s_and_b32 s28, s25, 0x8000
	s_xor_b32 s29, s28, 0x8000
	s_add_i32 s29, s29, vcc_hi
	s_mov_b32 m0, s29
	s_add_i32 vcc_lo, s29, 0x4000
	global_load_lds_dwordx4 v150, s[46:47]
	s_mov_b32 m0, vcc_lo
	s_add_i32 vcc_lo, s29, 0x1000
	global_load_lds_dwordx4 v151, s[46:47]
	s_mov_b32 m0, vcc_lo
	s_add_i32 vcc_lo, s29, 0x5000
	global_load_lds_dwordx4 v152, s[46:47]
	s_mov_b32 m0, vcc_lo
	s_add_i32 vcc_lo, s29, 0x2000
	global_load_lds_dwordx4 v153, s[46:47]
	s_mov_b32 m0, vcc_lo
	s_add_i32 vcc_lo, s29, 0x6000
	global_load_lds_dwordx4 v154, s[46:47]
	s_mov_b32 m0, vcc_lo
	s_add_i32 vcc_lo, s29, 0x3000
	global_load_lds_dwordx4 v155, s[46:47]
	s_mov_b32 m0, vcc_lo
	s_add_i32 vcc_lo, s29, 0x7000
	global_load_lds_dwordx4 v156, s[46:47]
	s_mov_b32 m0, vcc_lo
	s_nop 0
	global_load_lds_dwordx4 v157, s[46:47]
	v_add_u32_e32 v150, 0x80, v150
	v_add_u32_e32 v151, 0x80, v151
	v_add_u32_e32 v152, 0x80, v152
	v_add_u32_e32 v153, 0x80, v153
	v_add_u32_e32 v154, 0x80, v154
	v_add_u32_e32 v155, 0x80, v155
	v_add_u32_e32 v156, 0x80, v156
	v_add_u32_e32 v157, 0x80, v157
	v_add_u32_e32 v98, s28, v85
	v_add_u32_e32 v114, s28, v84
	v_add_u32_e32 v130, s28, v83
	v_add_u32_e32 v146, s28, v2
	ds_read_b128 v[86:89], v98
	ds_read_b128 v[90:93], v98 offset:2048
	ds_read_b128 v[94:97], v98 offset:4096
	ds_read_b128 v[98:101], v98 offset:6144
	ds_read_b128 v[102:105], v114 offset:16384
	ds_read_b128 v[106:109], v114 offset:18432
	ds_read_b128 v[110:113], v114 offset:20480
	ds_read_b128 v[114:117], v114 offset:22528
	ds_read_b128 v[118:121], v130
	ds_read_b128 v[122:125], v130 offset:2048
	ds_read_b128 v[126:129], v130 offset:4096
	ds_read_b128 v[130:133], v130 offset:6144
	ds_read_b128 v[134:137], v146 offset:16384
	ds_read_b128 v[138:141], v146 offset:18432
	ds_read_b128 v[142:145], v146 offset:20480
	ds_read_b128 v[146:149], v146 offset:22528
	s_waitcnt lgkmcnt(0)
	v_mfma_f32_16x16x32_bf16 v[64:67], v[102:105], v[86:89], v[64:67]
	v_mfma_f32_16x16x32_bf16 v[60:63], v[106:109], v[86:89], v[60:63]
	v_mfma_f32_16x16x32_bf16 v[56:59], v[110:113], v[86:89], v[56:59]
	v_mfma_f32_16x16x32_bf16 v[52:55], v[114:117], v[86:89], v[52:55]
	v_mfma_f32_16x16x32_bf16 v[48:51], v[102:105], v[90:93], v[48:51]
	v_mfma_f32_16x16x32_bf16 v[44:47], v[106:109], v[90:93], v[44:47]
	v_mfma_f32_16x16x32_bf16 v[40:43], v[110:113], v[90:93], v[40:43]
	v_mfma_f32_16x16x32_bf16 v[36:39], v[114:117], v[90:93], v[36:39]
	v_mfma_f32_16x16x32_bf16 v[32:35], v[102:105], v[94:97], v[32:35]
	v_mfma_f32_16x16x32_bf16 v[28:31], v[106:109], v[94:97], v[28:31]
	v_mfma_f32_16x16x32_bf16 v[24:27], v[110:113], v[94:97], v[24:27]
	v_mfma_f32_16x16x32_bf16 v[20:23], v[114:117], v[94:97], v[20:23]
	v_mfma_f32_16x16x32_bf16 v[16:19], v[102:105], v[98:101], v[16:19]
	v_mfma_f32_16x16x32_bf16 v[12:15], v[106:109], v[98:101], v[12:15]
	v_mfma_f32_16x16x32_bf16 v[8:11], v[110:113], v[98:101], v[8:11]
	v_mfma_f32_16x16x32_bf16 v[4:7], v[114:117], v[98:101], v[4:7]
	v_mfma_f32_16x16x32_bf16 v[64:67], v[134:137], v[118:121], v[64:67]
	v_mfma_f32_16x16x32_bf16 v[60:63], v[138:141], v[118:121], v[60:63]
	v_mfma_f32_16x16x32_bf16 v[56:59], v[142:145], v[118:121], v[56:59]
	v_mfma_f32_16x16x32_bf16 v[52:55], v[146:149], v[118:121], v[52:55]
	v_mfma_f32_16x16x32_bf16 v[48:51], v[134:137], v[122:125], v[48:51]
	v_mfma_f32_16x16x32_bf16 v[44:47], v[138:141], v[122:125], v[44:47]
	v_mfma_f32_16x16x32_bf16 v[40:43], v[142:145], v[122:125], v[40:43]
	v_mfma_f32_16x16x32_bf16 v[36:39], v[146:149], v[122:125], v[36:39]
	v_mfma_f32_16x16x32_bf16 v[32:35], v[134:137], v[126:129], v[32:35]
	v_mfma_f32_16x16x32_bf16 v[28:31], v[138:141], v[126:129], v[28:31]
	v_mfma_f32_16x16x32_bf16 v[24:27], v[142:145], v[126:129], v[24:27]
	v_mfma_f32_16x16x32_bf16 v[20:23], v[146:149], v[126:129], v[20:23]
	v_mfma_f32_16x16x32_bf16 v[16:19], v[134:137], v[130:133], v[16:19]
	v_mfma_f32_16x16x32_bf16 v[12:15], v[138:141], v[130:133], v[12:15]
	v_mfma_f32_16x16x32_bf16 v[8:11], v[142:145], v[130:133], v[8:11]
	v_mfma_f32_16x16x32_bf16 v[4:7], v[146:149], v[130:133], v[4:7]
	s_waitcnt vmcnt(0) lgkmcnt(0)
	s_barrier
	s_add_u32 s26, s26, 0x80
	s_addc_u32 s27, s27, 0
	s_add_i32 s25, s25, 0x8000
	s_cmpk_eq_i32 s26, 0x780
	s_cbranch_scc0 .LBB0_657
; __device__ __forceinline__ unsigned char* WS(const Params& p) { unsigned z = 0; asm volatile("" : "+s"(z)); return p.ws + z; }
; __device__ __forceinline__ unsigned pk2(float lo, float hi) { unsigned r; asm("v_cvt_pk_bf16_f32 %0, %1, %2" : "=v"(r) : "v"(lo), "v"(hi)); return r; }
; __device__ __forceinline__ void gemm_mainloop_d(const bf16_t* __restrict__ Ap, int lda, const bf16_t* __restrict__ Bt, int K,
;                                                 int m0, int n0, f32x4 (&acc)[4][4], char* lds) {
;     ...
;   for (int kt = 0; kt < nk; kt++) {
;     const int st = kt & 1;
;     if (kt + 1 < nk) dma(kt + 1, st ^ 1);
;     const char* la = lds + st * 32768; const char* lb = la + 16384;
;     bf16x8 af[2][4], bfv[2][4];
; #pragma unroll
;     for (int kc = 0; kc < 2; kc++) {
; #pragma unroll
;       for (int m = 0; m < 4; m++) { const int row = wr * 64 + m * 16 + fr; af[kc][m] = *(const bf16x8*)(la + (row * 8 + ((kc * 4 + fq) ^ ((row >> 1) & 7))) * 16); }
; #pragma unroll
;       for (int n = 0; n < 4; n++) { const int row = wc * 64 + n * 16 + fr; bfv[kc][n] = *(const bf16x8*)(lb + (row * 8 + ((kc * 4 + fq) ^ ((row >> 1) & 7))) * 16); }
;     }
;     __builtin_amdgcn_s_setprio(1);
; #pragma unroll
;     for (int kc = 0; kc < 2; kc++)
; #pragma unroll
;       for (int m = 0; m < 4; m++)
; #pragma unroll
;         for (int n = 0; n < 4; n++) acc[m][n] = __builtin_amdgcn_mfma_f32_16x16x32_bf16(bfv[kc][n], af[kc][m], acc[m][n], 0, 0, 0);
;     __builtin_amdgcn_s_setprio(0);
;     asm volatile("s_waitcnt vmcnt(0) lgkmcnt(0)" ::: "memory"); __builtin_amdgcn_s_barrier(); asm volatile("" ::: "memory");
; __device__ __forceinline__ void gemm_A(const Params& p, int item, char* lds) {
;     ...
;   const float* rssg = (const float*)(WS(p) + OFF_RSS) + m0;
;   bf16_t* P = (bf16_t*)(WS(p) + OFF_P);
; #pragma unroll
;   for (int m = 0; m < 4; m++) {
;     const int rl = wr * 64 + m * 16 + fr; const float r = rsqrtf(rssg[rl] * (1.f / 1024.f) + 1e-6f);
;     float sq = 0.f;
; #pragma unroll
;     for (int n = 0; n < 4; n++) {
;       const int col = n0 + wc * 64 + n * 16 + fq * 4;
;       if (col < PIN) { f32x4 v = acc[m][n] * r; u32x2 w; w[0] = pk2(v[0], v[1]); w[1] = pk2(v[2], v[3]); *(u32x2*)(P + (size_t)(m0 + rl) * PIN + col) = w;
;         const float b0 = bflo(w[0]), b1 = bfhi(w[0]), b2 = bflo(w[1]), b3 = bfhi(w[1]); sq += b0 * b0 + b1 * b1 + b2 * b2 + b3 * b3; }
	v_add_u32_e32 v0, 0, v85
	ds_read_b128 v[68:71], v0 offset:32768
	ds_read_b128 v[72:75], v0 offset:34816
	ds_read_b128 v[76:79], v0 offset:36864
	ds_read_b128 v[86:89], v0 offset:38912
	v_add_u32_e32 v0, 0, v84
	ds_read_b128 v[90:93], v0 offset:49152
	ds_read_b128 v[94:97], v0 offset:51200
	ds_read_b128 v[98:101], v0 offset:53248
	ds_read_b128 v[102:105], v0 offset:55296
	v_add_u32_e32 v0, 0, v83
	ds_read_b128 v[80:83], v0 offset:32768
	ds_read_b128 v[106:109], v0 offset:34816
	ds_read_b128 v[110:113], v0 offset:36864
	ds_read_b128 v[114:117], v0 offset:38912
	v_add_u32_e32 v0, 0, v2
	ds_read_b128 v[118:121], v0 offset:49152
	ds_read_b128 v[122:125], v0 offset:51200
	ds_read_b128 v[126:129], v0 offset:53248
	ds_read_b128 v[130:133], v0 offset:55296
	s_waitcnt lgkmcnt(0)
	v_mfma_f32_16x16x32_bf16 v[64:67], v[90:93], v[68:71], v[64:67]
	v_mfma_f32_16x16x32_bf16 v[60:63], v[94:97], v[68:71], v[60:63]
	v_mfma_f32_16x16x32_bf16 v[56:59], v[98:101], v[68:71], v[56:59]
	v_mfma_f32_16x16x32_bf16 v[52:55], v[102:105], v[68:71], v[52:55]
	v_mfma_f32_16x16x32_bf16 v[48:51], v[90:93], v[72:75], v[48:51]
	v_mfma_f32_16x16x32_bf16 v[44:47], v[94:97], v[72:75], v[44:47]
	v_mfma_f32_16x16x32_bf16 v[40:43], v[98:101], v[72:75], v[40:43]
	v_mfma_f32_16x16x32_bf16 v[36:39], v[102:105], v[72:75], v[36:39]
	v_mfma_f32_16x16x32_bf16 v[32:35], v[90:93], v[76:79], v[32:35]
	v_mfma_f32_16x16x32_bf16 v[28:31], v[94:97], v[76:79], v[28:31]
	v_mfma_f32_16x16x32_bf16 v[24:27], v[98:101], v[76:79], v[24:27]
	v_mfma_f32_16x16x32_bf16 v[20:23], v[102:105], v[76:79], v[20:23]
	v_mfma_f32_16x16x32_bf16 v[16:19], v[90:93], v[86:89], v[16:19]
	v_mfma_f32_16x16x32_bf16 v[12:15], v[94:97], v[86:89], v[12:15]
	v_mfma_f32_16x16x32_bf16 v[8:11], v[98:101], v[86:89], v[8:11]
	v_mfma_f32_16x16x32_bf16 v[4:7], v[102:105], v[86:89], v[4:7]
	v_mfma_f32_16x16x32_bf16 v[64:67], v[118:121], v[80:83], v[64:67]
	v_mfma_f32_16x16x32_bf16 v[60:63], v[122:125], v[80:83], v[60:63]
	v_mfma_f32_16x16x32_bf16 v[56:59], v[126:129], v[80:83], v[56:59]
	v_mfma_f32_16x16x32_bf16 v[52:55], v[130:133], v[80:83], v[52:55]
	v_mfma_f32_16x16x32_bf16 v[48:51], v[118:121], v[106:109], v[48:51]
	v_mfma_f32_16x16x32_bf16 v[44:47], v[122:125], v[106:109], v[44:47]
	v_mfma_f32_16x16x32_bf16 v[40:43], v[126:129], v[106:109], v[40:43]
	v_mfma_f32_16x16x32_bf16 v[36:39], v[130:133], v[106:109], v[36:39]
	v_mfma_f32_16x16x32_bf16 v[32:35], v[118:121], v[110:113], v[32:35]
	v_mfma_f32_16x16x32_bf16 v[28:31], v[122:125], v[110:113], v[28:31]
	v_mfma_f32_16x16x32_bf16 v[24:27], v[126:129], v[110:113], v[24:27]
	v_mfma_f32_16x16x32_bf16 v[20:23], v[130:133], v[110:113], v[20:23]
	v_mfma_f32_16x16x32_bf16 v[16:19], v[118:121], v[114:117], v[16:19]
	v_mfma_f32_16x16x32_bf16 v[12:15], v[122:125], v[114:117], v[12:15]
	v_mfma_f32_16x16x32_bf16 v[8:11], v[126:129], v[114:117], v[8:11]
	v_mfma_f32_16x16x32_bf16 v[4:7], v[130:133], v[114:117], v[4:7]
	v_mov_b32_e32 v2, v198
	s_mov_b32 s25, s89
	s_waitcnt vmcnt(0) lgkmcnt(0)
	s_barrier
	s_add_u32 s28, s46, s25
	s_addc_u32 s29, s47, 0
	s_ashr_i32 s25, s24, 31
	v_and_b32_e32 v0, 15, v2
	s_lshl_b64 s[26:27], s[24:25], 2
	v_ashrrev_i32_e32 v1, 1, v2
	s_movk_i32 s4, 0xffc0
	s_add_u32 s28, s28, s26
	v_and_or_b32 v0, v1, s4, v0
	s_addc_u32 s29, s29, s27
	v_ashrrev_i32_e32 v1, 31, v0
	v_lshl_add_u64 v[70:71], v[0:1], 2, s[28:29]
	s_mov_b32 s28, 0xff8c000
	v_add_co_u32_e32 v68, vcc, s28, v70
	s_mov_b32 s25, s89
	s_nop 0
	v_addc_co_u32_e32 v69, vcc, 0, v71, vcc
	global_load_dword v69, v[68:69], off
	v_and_b32_e32 v68, 64, v2
	v_bfe_u32 v2, v2, 4, 2
	v_lshlrev_b32_e32 v72, 2, v2
	v_or3_b32 v68, v72, v68, s3
	s_add_u32 s3, s46, s25
	s_addc_u32 s25, s47, 0
	s_add_u32 s30, s3, 0x768000
	s_addc_u32 s31, s25, 0
	v_add_u32_e32 v74, s24, v0
	v_mov_b32_e32 v76, 0
	v_cmp_gt_i32_e64 s[34:35], s78, v68
	s_waitcnt vmcnt(0)
	v_fmamk_f32 v69, v69, 0x3a800000, v200
	v_mul_f32_e32 v72, 0x4b800000, v69
	v_cmp_gt_f32_e32 vcc, s83, v69
	s_nop 1
	v_cndmask_b32_e32 v69, v69, v72, vcc
	v_rsq_f32_e32 v69, v69
	v_mov_b64_e32 v[72:73], s[30:31]
	v_mad_i64_i32 v[72:73], s[28:29], v74, s69, v[72:73]
	v_mul_f32_e32 v74, 0x45800000, v69
	v_cndmask_b32_e32 v74, v69, v74, vcc
	v_mov_b32_e32 v75, v74
	v_ashrrev_i32_e32 v69, 31, v68
	s_and_saveexec_b64 s[28:29], s[34:35]
	s_cbranch_execz .LBB0_660
	v_mov_b32_e32 v76, v74
	v_mov_b32_e32 v77, v74
	v_pk_mul_f32 v[66:67], v[66:67], v[76:77]
	v_pk_mul_f32 v[64:65], v[64:65], v[74:75]
	s_nop 0
	v_cvt_pk_bf16_f32 v64, v64, v65
	v_cvt_pk_bf16_f32 v65, v66, v67
	v_lshl_add_u64 v[66:67], v[68:69], 1, v[72:73]
	global_store_dwordx2 v[66:67], v[64:65], off
	v_lshlrev_b32_e32 v66, 16, v64
	v_and_b32_e32 v67, 0xffff0000, v64
	v_pk_mul_f32 v[66:67], v[66:67], v[66:67]
	v_and_b32_e32 v64, 0xffff0000, v65
	v_lshlrev_b32_e32 v65, 16, v65
	v_pk_mul_f32 v[64:65], v[64:65], v[64:65]
	v_add_f32_e32 v66, v66, v67
	v_add_f32_e32 v65, v66, v65
	v_add_f32_e32 v76, v64, v65
